# on top of lean in-proj epilogue: attention K/V/Q staging loads issued together before one wait (was 2-4 serialized round trips per unit), GEMM prologue second K-tile loads issued before the first wait
# speedup vs baseline: 1.0028x; 1.0028x over previous
; #define LAS __attribute__((address_space(3)))
; #define GAS __attribute__((address_space(1)))
; DI void phase_attn(const Ctx& C, bf16_t* Z, float* lse, bool dry) {
;     ...
;         const int uid = ui < upc ? C.bid * upc + ui : C.gsz * upc + C.bid;
;         const int j = uid & 31, head = (uid >> 5) % 12, bl = uid / 384;
;         const int g = head >> 2, dsh = 2 * g, nsh = 5 - dsh;
;         const int r = j >> nsh, n = j & ((1 << nsh) - 1);
;         const size_t rowb = (size_t)bl * SEQ + r;
;         const bool reuse = (ui > 0) && (ui < upc) && (n > 0);
;         cslot = reuse ? (cslot ^ 1) : 1;
;         const int rot = 128 * (1 - cslot), rot16 = rot >> 4;
; #pragma unroll
;         for (int cc = 0; cc < 4; ++cc) {
;             if (cc < 2 && reuse) continue;
;             const int c = tid + cc * 512, kj = c >> 3, ch = c & 7, mm = (n - 1) * 128 + kj, pk = (kj + rot) & 255;
;             u32x4 kv = {0u, 0u, 0u, 0u}, vv = {0u, 0u, 0u, 0u};
;             if (mm >= 0) { const bf16_t* p = Z + (rowb + ((size_t)mm << dsh)) * ZW + head * 64 + ch * 8; kv = __builtin_nontemporal_load((const GAS u32x4*)(p + CK)); vv = __builtin_nontemporal_load((const GAS u32x4*)(p + CV)); }
;             *(LAS u32x4*)(Ks + pk * 72 + ch * 8) = kv;
;             LAS bf16_t* vp = Vt + (ch * 8) * 264 + (pk ^ (ch << 3));
;             vp[0 * 264] = (bf16_t)(vv.x & 0xffffu); vp[1 * 264] = (bf16_t)(vv.x >> 16);
;             vp[2 * 264] = (bf16_t)(vv.y & 0xffffu); vp[3 * 264] = (bf16_t)(vv.y >> 16);
;             vp[4 * 264] = (bf16_t)(vv.z & 0xffffu); vp[5 * 264] = (bf16_t)(vv.z >> 16);
;             vp[6 * 264] = (bf16_t)(vv.w & 0xffffu); vp[7 * 264] = (bf16_t)(vv.w >> 16);
;         }
;         const int qi = 16 * w + fr; const size_t qrow = rowb + ((size_t)(n * 128 + qi) << dsh);
;         bf16_t* qp = Z + qrow * ZW + head * 64;
;         const bf16x8 qf0 = __builtin_nontemporal_load((const GAS bf16x8*)(qp + 8 * fq)), qf1 = __builtin_nontemporal_load((const GAS bf16x8*)(qp + 32 + 8 * fq));
.LBB0_205:
	s_mul_i32 s2, s34, s47
	s_add_i32 s12, s2, s49
	s_cmp_lt_i32 s49, s34
	s_cselect_b64 s[18:19], -1, 0
	s_and_b64 s[2:3], s[18:19], exec
	s_cselect_b32 s2, s12, s45
	s_ashr_i32 s12, s2, 5
	s_mul_hi_i32 s13, s12, 0x2aaaaaab
	s_lshr_b32 s14, s13, 31
	s_lshr_b32 s13, s13, 1
	s_add_i32 s13, s13, s14
	s_and_b32 s3, s2, 31
	s_mul_i32 s13, s13, 12
	s_mul_hi_i32 s2, s2, 0x2aaaaaab
	s_sub_i32 s12, s12, s13
	s_lshr_b32 s13, s2, 31
	s_ashr_i32 s2, s2, 6
	s_add_i32 s14, s2, s13
	s_ashr_i32 s2, s12, 1
	s_and_b32 s2, s2, -2
	s_sub_i32 s13, 5, s2
	s_ashr_i32 s15, s14, 31
	s_lshr_b32 s20, s3, s13
	s_lshl_b32 s13, -1, s13
	s_lshl_b64 s[16:17], s[14:15], 12
	s_andn2_b32 s13, s3, s13
	s_or_b32 s16, s16, s20
	s_cmp_lg_u32 s49, 0
	s_cselect_b64 s[20:21], -1, 0
	s_cmp_lg_u32 s13, 0
	s_cselect_b64 s[14:15], -1, 0
	s_and_b64 s[20:21], s[20:21], s[14:15]
	s_and_b64 s[18:19], s[20:21], s[18:19]
	s_xor_b32 s3, s53, 1
	s_and_b64 vcc, s[18:19], exec
	s_cselect_b32 s53, s3, 1
	s_lshl_b32 s18, s12, 6
	s_lshl_b32 s3, s53, 7
	s_lshl_b32 s40, s13, 7
	s_ashr_i32 s19, s18, 31
	s_sub_i32 s3, 0x80, s3
	s_add_i32 s13, s40, 0xffffff80
	v_lshl_add_u64 v[16:17], s[18:19], 1, v[24:25]
	s_mov_b64 s[98:99], vcc
	s_movk_i32 s24, 0x90
	s_movk_i32 s25, 0xff
	s_cbranch_vccnz .Lattn_ld2
	v_add_u32_e32 v192, s13, v40
	v_cmp_lt_i32_e32 vcc, -1, v192
	v_mov_b32_e32 v144, 0
	v_mov_b32_e32 v145, 0
	v_mov_b32_e32 v146, 0
	v_mov_b32_e32 v147, 0
	v_mov_b32_e32 v148, 0
	v_mov_b32_e32 v149, 0
	v_mov_b32_e32 v150, 0
	v_mov_b32_e32 v151, 0
	s_and_saveexec_b64 s[20:21], vcc
	v_lshlrev_b64 v[176:177], s2, v[192:193]
	v_lshl_add_u64 v[176:177], v[176:177], 0, s[16:17]
	v_mad_u64_u32 v[178:179], vcc, v176, s51, v[16:17]
	v_mov_b32_e32 v176, v179
	v_mad_u64_u32 v[176:177], vcc, v177, s51, v[176:177]
	v_mov_b32_e32 v179, v176
	global_load_dwordx4 v[144:147], v[178:179], off offset:1536 nt
	global_load_dwordx4 v[148:151], v[178:179], off offset:3072 nt
	s_or_b64 exec, exec, s[20:21]
	v_add_u32_e32 v192, s13, v41
	v_cmp_lt_i32_e32 vcc, -1, v192
	v_mov_b32_e32 v152, 0
	v_mov_b32_e32 v153, 0
	v_mov_b32_e32 v154, 0
	v_mov_b32_e32 v155, 0
	v_mov_b32_e32 v156, 0
	v_mov_b32_e32 v157, 0
	v_mov_b32_e32 v158, 0
	v_mov_b32_e32 v159, 0
	s_and_saveexec_b64 s[20:21], vcc
	v_lshlrev_b64 v[176:177], s2, v[192:193]
	v_lshl_add_u64 v[176:177], v[176:177], 0, s[16:17]
	v_mad_u64_u32 v[178:179], vcc, v176, s51, v[16:17]
	v_mov_b32_e32 v176, v179
	v_mad_u64_u32 v[176:177], vcc, v177, s51, v[176:177]
	v_mov_b32_e32 v179, v176
	global_load_dwordx4 v[152:155], v[178:179], off offset:1536 nt
	global_load_dwordx4 v[156:159], v[178:179], off offset:3072 nt
	s_or_b64 exec, exec, s[20:21]
.Lattn_ld2:
	v_add_u32_e32 v192, s13, v42
	v_cmp_lt_i32_e32 vcc, -1, v192
	v_mov_b32_e32 v160, 0
	v_mov_b32_e32 v161, 0
	v_mov_b32_e32 v162, 0
	v_mov_b32_e32 v163, 0
	v_mov_b32_e32 v164, 0
	v_mov_b32_e32 v165, 0
	v_mov_b32_e32 v166, 0
	v_mov_b32_e32 v167, 0
	s_and_saveexec_b64 s[20:21], vcc
	v_lshlrev_b64 v[176:177], s2, v[192:193]
	v_lshl_add_u64 v[176:177], v[176:177], 0, s[16:17]
	v_mad_u64_u32 v[178:179], vcc, v176, s51, v[16:17]
	v_mov_b32_e32 v176, v179
	v_mad_u64_u32 v[176:177], vcc, v177, s51, v[176:177]
	v_mov_b32_e32 v179, v176
	global_load_dwordx4 v[160:163], v[178:179], off offset:1536 nt
	global_load_dwordx4 v[164:167], v[178:179], off offset:3072 nt
	s_or_b64 exec, exec, s[20:21]
	v_add_u32_e32 v192, s13, v43
	v_cmp_lt_i32_e32 vcc, -1, v192
	v_mov_b32_e32 v168, 0
	v_mov_b32_e32 v169, 0
	v_mov_b32_e32 v170, 0
	v_mov_b32_e32 v171, 0
	v_mov_b32_e32 v172, 0
	v_mov_b32_e32 v173, 0
	v_mov_b32_e32 v174, 0
	v_mov_b32_e32 v175, 0
	s_and_saveexec_b64 s[20:21], vcc
	v_lshlrev_b64 v[176:177], s2, v[192:193]
	v_lshl_add_u64 v[176:177], v[176:177], 0, s[16:17]
	v_mad_u64_u32 v[178:179], vcc, v176, s51, v[16:17]
	v_mov_b32_e32 v176, v179
	v_mad_u64_u32 v[176:177], vcc, v177, s51, v[176:177]
	v_mov_b32_e32 v179, v176
	global_load_dwordx4 v[168:171], v[178:179], off offset:1536 nt
	global_load_dwordx4 v[172:175], v[178:179], off offset:3072 nt
	s_or_b64 exec, exec, s[20:21]
	v_add_u32_e32 v192, s40, v37
	v_lshlrev_b64 v[0:1], s2, v[192:193]
	v_lshl_add_u64 v[30:31], v[0:1], 0, s[16:17]
	v_readlane_b32 s16, v253, 51
	v_readlane_b32 s17, v253, 52
	v_mov_b32_e32 v29, v193
	v_mov_b64_e32 v[0:1], s[16:17]
	v_mad_u64_u32 v[0:1], s[16:17], v30, s51, v[0:1]
	v_mov_b32_e32 v2, v1
	v_mad_u64_u32 v[2:3], s[16:17], v31, s51, v[2:3]
	v_mov_b32_e32 v1, v2
	v_lshl_add_u64 v[32:33], s[18:19], 1, v[0:1]
	v_lshl_add_u64 v[0:1], v[32:33], 0, v[28:29]
	global_load_dwordx4 v[4:7], v[0:1], off nt
	s_nop 0
	global_load_dwordx4 v[0:3], v[0:1], off offset:64 nt
	s_lshr_b32 s13, s3, 4
	s_movk_i32 s2, 0xff
	v_readlane_b32 s20, v253, 32
	s_movk_i32 s21, 0x90
	s_or_b32 s2, s13, s20
	s_lshl_b32 s16, s2, 4
	s_waitcnt vmcnt(0)
	s_and_b64 vcc, exec, s[98:99]
	s_cbranch_vccnz .Lattn_wr2
	v_add_u32_e32 v181, s3, v40
	v_and_b32_e32 v180, 0xff, v181
	v_mad_u32_u24 v180, v180, s24, v35
	v_bitop3_b32 v181, v181, v34, s25 bitop3:0x6c
	v_lshl_add_u32 v181, v181, 1, v36
	ds_write_b128 v180, v[144:147]
	ds_write_b16 v181, v148 offset:36864
	ds_write_b16_d16_hi v181, v148 offset:37392
	ds_write_b16 v181, v149 offset:37920
	ds_write_b16_d16_hi v181, v149 offset:38448
	ds_write_b16 v181, v150 offset:38976
	ds_write_b16_d16_hi v181, v150 offset:39504
	ds_write_b16 v181, v151 offset:40032
	ds_write_b16_d16_hi v181, v151 offset:40560
	v_add_u32_e32 v183, s3, v41
	v_and_b32_e32 v182, 0xff, v183
	v_mad_u32_u24 v182, v182, s24, v35
	v_bitop3_b32 v183, v183, v34, s25 bitop3:0x6c
	v_lshl_add_u32 v183, v183, 1, v36
	ds_write_b128 v182, v[152:155]
	ds_write_b16 v183, v156 offset:36864
	ds_write_b16_d16_hi v183, v156 offset:37392
	ds_write_b16 v183, v157 offset:37920
	ds_write_b16_d16_hi v183, v157 offset:38448
	ds_write_b16 v183, v158 offset:38976
	ds_write_b16_d16_hi v183, v158 offset:39504
	ds_write_b16 v183, v159 offset:40032
	ds_write_b16_d16_hi v183, v159 offset:40560
; #define LAS __attribute__((address_space(3)))
; DI void phase_attn(const Ctx& C, bf16_t* Z, float* lse, bool dry) {
;     ...
;             *(LAS u32x4*)(Ks + pk * 72 + ch * 8) = kv;
;             LAS bf16_t* vp = Vt + (ch * 8) * 264 + (pk ^ (ch << 3));
;             vp[0 * 264] = (bf16_t)(vv.x & 0xffffu); vp[1 * 264] = (bf16_t)(vv.x >> 16);
;             vp[2 * 264] = (bf16_t)(vv.y & 0xffffu); vp[3 * 264] = (bf16_t)(vv.y >> 16);
;             vp[4 * 264] = (bf16_t)(vv.z & 0xffffu); vp[5 * 264] = (bf16_t)(vv.z >> 16);
;             vp[6 * 264] = (bf16_t)(vv.w & 0xffffu); vp[7 * 264] = (bf16_t)(vv.w >> 16);
;     ...
;         __syncthreads();
;         const int t0 = w < 6 ? w : 6;
;         f32x4 st[10];
; #pragma unroll
;         for (int x = 0; x < 10; ++x) {
;             const LAS bf16_t* kp = Ks + (16 * ((t0 + x + rot16) & 15) + fr) * 72 + 8 * fq;
;             const bf16x8 a0 = *(const LAS bf16x8*)kp, a1 = *(const LAS bf16x8*)(kp + 32);
;             f32x4 acc = {0.f, 0.f, 0.f, 0.f};
;             acc = __builtin_amdgcn_mfma_f32_16x16x32_bf16(a0, qf0, acc, 0, 0, 0);
;             acc = __builtin_amdgcn_mfma_f32_16x16x32_bf16(a1, qf1, acc, 0, 0, 0);
;             st[x] = acc;
;         }
;         float mx = -INFINITY;
; #pragma unroll
;         for (int x = 0; x < 10; ++x)
; #pragma unroll
;             for (int i = 0; i < 4; ++i) {
;                 const int kj = 16 * (t0 + x) + 4 * fq + i, dist = qi + 128 - kj;
;                 const bool valid = (dist >= 0) && (dist <= 128) && (n > 0 || kj >= 128);
;                 const float s = valid ? st[x][i] : -INFINITY; st[x][i] = s; mx = fmaxf(mx, s);
;             }
.Lattn_wr2:
	v_add_u32_e32 v181, s3, v42
	v_and_b32_e32 v180, 0xff, v181
	v_mad_u32_u24 v180, v180, s24, v35
	v_bitop3_b32 v181, v181, v34, s25 bitop3:0x6c
	v_lshl_add_u32 v181, v181, 1, v36
	ds_write_b128 v180, v[160:163]
	ds_write_b16 v181, v164 offset:36864
	ds_write_b16_d16_hi v181, v164 offset:37392
	ds_write_b16 v181, v165 offset:37920
	ds_write_b16_d16_hi v181, v165 offset:38448
	ds_write_b16 v181, v166 offset:38976
	ds_write_b16_d16_hi v181, v166 offset:39504
	ds_write_b16 v181, v167 offset:40032
	ds_write_b16_d16_hi v181, v167 offset:40560
	v_add_u32_e32 v183, s3, v43
	v_and_b32_e32 v182, 0xff, v183
	v_mad_u32_u24 v182, v182, s24, v35
	v_bitop3_b32 v183, v183, v34, s25 bitop3:0x6c
	v_lshl_add_u32 v183, v183, 1, v36
	ds_write_b128 v182, v[168:171]
	ds_write_b16 v183, v172 offset:36864
	ds_write_b16_d16_hi v183, v172 offset:37392
	ds_write_b16 v183, v173 offset:37920
	ds_write_b16_d16_hi v183, v173 offset:38448
	ds_write_b16 v183, v174 offset:38976
	ds_write_b16_d16_hi v183, v174 offset:39504
	ds_write_b16 v183, v175 offset:40032
	ds_write_b16_d16_hi v183, v175 offset:40560
	v_or_b32_e32 v8, s16, v27
	v_mad_u32_u24 v12, v8, s21, v38
	s_waitcnt lgkmcnt(0)
	s_barrier
	ds_read_b128 v[8:11], v12
	ds_read_b128 v[12:15], v12 offset:64
	v_readlane_b32 s2, v253, 59
	v_readlane_b32 s3, v253, 60
	s_and_b64 vcc, s[2:3], s[14:15]
	v_readlane_b32 s2, v253, 55
	v_mov_b32_e32 v113, 0xff800000
	v_readlane_b32 s3, v253, 56
	v_readlane_b32 s18, v254, 6
	v_readlane_b32 s19, v254, 7
	s_add_i32 s17, s16, 48
	s_and_b32 s17, s17, 0xf0
	v_lshlrev_b32_e32 v192, 1, v26
	s_waitcnt vmcnt(1) lgkmcnt(1)
	v_mfma_f32_16x16x32_bf16 v[8:11], v[8:11], v[4:7], 0
	s_waitcnt vmcnt(0) lgkmcnt(0)
	v_mfma_f32_16x16x32_bf16 v[8:11], v[12:15], v[0:3], v[8:11]
	s_nop 7
	v_cndmask_b32_e32 v8, v113, v8, vcc
	s_and_b64 vcc, s[2:3], s[14:15]
	s_add_i32 s2, s16, 16
	s_and_b32 s2, s2, 0xf0
	v_or_b32_e32 v12, s2, v27
	v_mad_u32_u24 v16, v12, s21, v38
	ds_read_b128 v[12:15], v16
	ds_read_b128 v[16:19], v16 offset:64
	v_readlane_b32 s2, v253, 57
	s_waitcnt lgkmcnt(1)
	v_mfma_f32_16x16x32_bf16 v[12:15], v[12:15], v[4:7], 0
	v_readlane_b32 s3, v253, 58
	v_cndmask_b32_e32 v9, v113, v9, vcc
	s_and_b64 vcc, s[2:3], s[14:15]
	v_readlane_b32 s2, v253, 53
	v_readlane_b32 s3, v253, 54
	v_cndmask_b32_e32 v10, v113, v10, vcc
	s_and_b64 vcc, s[2:3], s[14:15]
	v_readlane_b32 s2, v254, 4
	s_waitcnt lgkmcnt(0)
	v_mfma_f32_16x16x32_bf16 v[12:15], v[16:19], v[0:3], v[12:15]
	v_readlane_b32 s3, v254, 5
	v_cndmask_b32_e32 v11, v113, v11, vcc
	s_and_b64 vcc, s[2:3], s[14:15]
	v_readlane_b32 s2, v254, 8
	v_readlane_b32 s3, v254, 9
	s_or_b64 s[2:3], s[2:3], s[14:15]
	s_nop 1
	v_cndmask_b32_e32 v12, v113, v12, vcc
	s_and_b64 vcc, s[18:19], s[2:3]
	s_add_i32 s2, s16, 32
	s_and_b32 s2, s2, 0xf0
	v_or_b32_e32 v16, s2, v27
	v_mad_u32_u24 v20, v16, s21, v38
	ds_read_b128 v[16:19], v20
	ds_read_b128 v[20:23], v20 offset:64
	s_waitcnt lgkmcnt(1)
	v_mfma_f32_16x16x32_bf16 v[16:19], v[16:19], v[4:7], 0
	v_readlane_b32 s2, v254, 10
	v_readlane_b32 s3, v254, 11
	v_cndmask_b32_e32 v13, v113, v13, vcc
	s_and_b64 vcc, s[2:3], s[14:15]
	v_readlane_b32 s2, v254, 12
	s_waitcnt lgkmcnt(0)
	v_mfma_f32_16x16x32_bf16 v[16:19], v[20:23], v[0:3], v[16:19]
	v_or_b32_e32 v20, s17, v27
	v_readlane_b32 s3, v254, 13
	v_mad_u32_u24 v29, v20, s21, v38
	v_cndmask_b32_e32 v14, v113, v14, vcc
	s_and_b64 vcc, s[2:3], s[14:15]
	v_readlane_b32 s2, v253, 13
	ds_read_b128 v[20:23], v29
	ds_read_b128 v[48:51], v29 offset:64
	v_readlane_b32 s3, v253, 14
	v_readlane_b32 s18, v254, 14
	s_or_b64 s[2:3], s[2:3], s[14:15]
	v_readlane_b32 s19, v254, 15
	v_cndmask_b32_e32 v15, v113, v15, vcc
	s_and_b64 vcc, s[18:19], s[2:3]
	v_readlane_b32 s18, v254, 18
	v_cndmask_b32_e32 v16, v113, v16, vcc
	v_readlane_b32 s19, v254, 19
	v_readlane_b32 vcc_lo, v254, 16
	s_waitcnt lgkmcnt(1)
	v_mfma_f32_16x16x32_bf16 v[20:23], v[20:23], v[4:7], 0
	s_add_i32 s17, s16, 64
	s_or_b64 s[18:19], s[18:19], s[14:15]
	v_readlane_b32 vcc_hi, v254, 17
	s_and_b32 s17, s17, 0xf0
	s_and_b64 vcc, vcc, s[18:19]
	v_readlane_b32 s18, v254, 20
	v_or_b32_e32 v29, s17, v27
	v_readlane_b32 s19, v254, 21
	v_mad_u32_u24 v29, v29, s21, v38
	v_cndmask_b32_e32 v17, v113, v17, vcc
	s_and_b64 vcc, s[18:19], s[2:3]
	v_readlane_b32 s18, v254, 22
	s_waitcnt lgkmcnt(0)
	v_mfma_f32_16x16x32_bf16 v[20:23], v[48:51], v[0:3], v[20:23]
	ds_read_b128 v[48:51], v29
	ds_read_b128 v[52:55], v29 offset:64
	v_readlane_b32 s19, v254, 23
	v_cndmask_b32_e32 v18, v113, v18, vcc
	s_and_b64 vcc, s[18:19], s[2:3]
	v_readlane_b32 s2, v253, 16
	v_readlane_b32 s3, v253, 17
	v_readlane_b32 s18, v254, 24
	s_or_b64 s[2:3], s[2:3], s[14:15]
	v_readlane_b32 s19, v254, 25
	s_waitcnt lgkmcnt(1)
	v_mfma_f32_16x16x32_bf16 v[48:51], v[48:51], v[4:7], 0
	s_add_i32 s17, s16, 0x50
	v_cndmask_b32_e32 v19, v113, v19, vcc
	s_and_b64 vcc, s[18:19], s[2:3]
	v_readlane_b32 s18, v254, 28
	s_and_b32 s17, s17, 0xf0
	v_cndmask_b32_e32 v20, v113, v20, vcc
	v_readlane_b32 s19, v254, 29
	v_readlane_b32 vcc_lo, v254, 26
	v_or_b32_e32 v29, s17, v27
	s_or_b64 s[18:19], s[18:19], s[14:15]
	v_readlane_b32 vcc_hi, v254, 27
	v_mad_u32_u24 v29, v29, s21, v38
	s_and_b64 vcc, vcc, s[18:19]
	v_readlane_b32 s18, v254, 30
	s_waitcnt lgkmcnt(0)
	v_mfma_f32_16x16x32_bf16 v[50:53], v[52:55], v[0:3], v[48:51]
	ds_read_b128 v[54:57], v29
	ds_read_b128 v[58:61], v29 offset:64
	v_readlane_b32 s19, v254, 31
	v_cndmask_b32_e32 v21, v113, v21, vcc
	s_and_b64 vcc, s[18:19], s[2:3]
	v_readlane_b32 s18, v254, 32
	v_readlane_b32 s19, v254, 33
	v_cndmask_b32_e32 v22, v113, v22, vcc
	s_and_b64 vcc, s[18:19], s[2:3]
	v_readlane_b32 s2, v253, 20
	s_waitcnt lgkmcnt(1)
; #define LAS __attribute__((address_space(3)))
; DI float max_xor32(float v) { auto rr = __builtin_amdgcn_permlane32_swap(__float_as_uint(v), __float_as_uint(v), false, false); return fmaxf(__uint_as_float(rr[0]), __uint_as_float(rr[1])); }
; DI void phase_attn(const Ctx& C, bf16_t* Z, float* lse, bool dry) {
;     ...
; #pragma unroll
;         for (int x = 0; x < 10; ++x) {
;             const LAS bf16_t* kp = Ks + (16 * ((t0 + x + rot16) & 15) + fr) * 72 + 8 * fq;
;             const bf16x8 a0 = *(const LAS bf16x8*)kp, a1 = *(const LAS bf16x8*)(kp + 32);
;             f32x4 acc = {0.f, 0.f, 0.f, 0.f};
;             acc = __builtin_amdgcn_mfma_f32_16x16x32_bf16(a0, qf0, acc, 0, 0, 0);
;             acc = __builtin_amdgcn_mfma_f32_16x16x32_bf16(a1, qf1, acc, 0, 0, 0);
;             st[x] = acc;
;         }
;         float mx = -INFINITY;
; #pragma unroll
;         for (int x = 0; x < 10; ++x)
; #pragma unroll
;             for (int i = 0; i < 4; ++i) {
;                 const int kj = 16 * (t0 + x) + 4 * fq + i, dist = qi + 128 - kj;
;                 const bool valid = (dist >= 0) && (dist <= 128) && (n > 0 || kj >= 128);
;                 const float s = valid ? st[x][i] : -INFINITY; st[x][i] = s; mx = fmaxf(mx, s);
;             }
;         mx = fmaxf(mx, lane_xor<16>(mx)); mx = max_xor32(mx);
	v_mfma_f32_16x16x32_bf16 v[54:57], v[54:57], v[4:7], 0
	s_add_i32 s17, s16, 0x60
	v_readlane_b32 s3, v253, 21
	v_readlane_b32 s18, v254, 34
	s_and_b32 s17, s17, 0xf0
	s_or_b64 s[2:3], s[2:3], s[14:15]
	v_readlane_b32 s19, v254, 35
	v_or_b32_e32 v29, s17, v27
	v_cndmask_b32_e32 v23, v113, v23, vcc
	s_and_b64 vcc, s[18:19], s[2:3]
	v_mad_u32_u24 v29, v29, s21, v38
	v_cndmask_b32_e32 v48, v113, v50, vcc
	v_readlane_b32 vcc_lo, v254, 36
	s_waitcnt lgkmcnt(0)
	v_mfma_f32_16x16x32_bf16 v[54:57], v[58:61], v[0:3], v[54:57]
	ds_read_b128 v[58:61], v29
	ds_read_b128 v[62:65], v29 offset:64
	s_or_b64 s[18:19], s[22:23], s[14:15]
	v_readlane_b32 vcc_hi, v254, 37
	s_and_b64 vcc, vcc, s[18:19]
	s_waitcnt lgkmcnt(1)
	v_mfma_f32_16x16x32_bf16 v[58:61], v[58:61], v[4:7], 0
	v_cndmask_b32_e32 v49, v113, v51, vcc
	s_and_b64 vcc, s[6:7], s[2:3]
	v_cndmask_b32_e32 v51, v113, v52, vcc
	s_and_b64 vcc, s[8:9], s[2:3]
	v_readlane_b32 s2, v253, 23
	s_add_i32 s17, s16, 0x70
	v_readlane_b32 s3, v253, 24
	s_and_b32 s17, s17, 0xf0
	s_or_b64 s[2:3], s[2:3], s[14:15]
	v_or_b32_e32 v29, s17, v27
	v_cndmask_b32_e32 v50, v113, v53, vcc
	s_and_b64 vcc, s[10:11], s[2:3]
	s_or_b64 s[18:19], s[60:61], s[14:15]
	v_mad_u32_u24 v29, v29, s21, v38
	v_cndmask_b32_e32 v52, v113, v54, vcc
	s_and_b64 vcc, s[58:59], s[18:19]
	s_waitcnt lgkmcnt(0)
	v_mfma_f32_16x16x32_bf16 v[58:61], v[62:65], v[0:3], v[58:61]
	ds_read_b128 v[62:65], v29
	ds_read_b128 v[66:69], v29 offset:64
	v_cndmask_b32_e32 v53, v113, v55, vcc
	s_and_b64 vcc, s[62:63], s[2:3]
	v_cndmask_b32_e32 v55, v113, v56, vcc
	s_and_b64 vcc, s[64:65], s[2:3]
	v_readlane_b32 s2, v253, 27
	v_readlane_b32 s3, v253, 28
	s_or_b64 s[2:3], s[2:3], s[14:15]
	s_waitcnt lgkmcnt(1)
	v_mfma_f32_16x16x32_bf16 v[62:65], v[62:65], v[4:7], 0
	v_cndmask_b32_e32 v54, v113, v57, vcc
	s_and_b64 vcc, s[66:67], s[2:3]
	s_or_b64 s[18:19], s[70:71], s[14:15]
	v_cndmask_b32_e32 v56, v113, v58, vcc
	s_and_b64 vcc, s[68:69], s[18:19]
	v_cndmask_b32_e32 v57, v113, v59, vcc
	s_and_b64 vcc, s[72:73], s[2:3]
	v_cndmask_b32_e32 v59, v113, v60, vcc
	s_and_b64 vcc, s[74:75], s[2:3]
	s_waitcnt lgkmcnt(0)
	v_mfma_f32_16x16x32_bf16 v[62:65], v[66:69], v[0:3], v[62:65]
	v_readlane_b32 s2, v253, 30
	v_readlane_b32 s3, v253, 31
	s_or_b64 s[2:3], s[2:3], s[14:15]
	v_cndmask_b32_e32 v58, v113, v61, vcc
	s_and_b64 vcc, s[76:77], s[2:3]
	s_or_b64 s[14:15], s[80:81], s[14:15]
	s_nop 1
	v_cndmask_b32_e32 v60, v113, v62, vcc
	s_and_b64 vcc, s[78:79], s[14:15]
	v_cndmask_b32_e32 v61, v113, v63, vcc
	s_and_b64 vcc, s[82:83], s[2:3]
	v_cndmask_b32_e32 v63, v113, v64, vcc
	s_and_b64 vcc, s[84:85], s[2:3]
	v_cndmask_b32_e32 v62, v113, v65, vcc
	v_mov_b32_e32 v65, 0x80
	v_bitop3_b32 v65, s16, v65, v27 bitop3:0x36
	v_mad_u32_u24 v65, v65, s21, v38
	ds_read_b128 v[78:81], v65
	ds_read_b128 v[82:85], v65 offset:64
	s_add_i32 s2, s16, 0x90
	s_waitcnt lgkmcnt(1)
	v_mfma_f32_16x16x32_bf16 v[78:81], v[78:81], v[4:7], 0
	s_and_b32 s2, s2, 0xf0
	v_or_b32_e32 v64, s2, v27
	v_mad_u32_u24 v64, v64, s21, v38
	s_waitcnt lgkmcnt(0)
	v_mfma_f32_16x16x32_bf16 v[78:81], v[82:85], v[0:3], v[78:81]
	ds_read_b128 v[82:85], v64
	ds_read_b128 v[86:89], v64 offset:64
	s_mov_b32 s2, 0xff800000
	v_max3_f32 v29, v8, s2, v9
	s_waitcnt lgkmcnt(1)
	v_mfma_f32_16x16x32_bf16 v[4:7], v[82:85], v[4:7], 0
	s_or_b32 s2, s13, 1
	s_add_i32 s3, s2, s20
	s_lshl_b32 s3, s3, 4
	s_waitcnt lgkmcnt(0)
	v_mfma_f32_16x16x32_bf16 v[0:3], v[86:89], v[0:3], v[4:7]
	v_bitop3_b32 v66, s16, v39, v26 bitop3:0x36
	s_and_b32 s3, s3, 0xf0
	v_bitop3_b32 v73, s3, v39, v26 bitop3:0x36
	v_max3_f32 v4, v29, v10, v11
	v_max3_f32 v4, v4, v12, v13
	v_max3_f32 v4, v4, v14, v15
	v_max3_f32 v4, v4, v16, v17
	v_max3_f32 v4, v4, v18, v19
	v_max3_f32 v4, v4, v20, v21
	v_max3_f32 v4, v4, v22, v23
	v_max3_f32 v4, v4, v48, v49
	v_max3_f32 v4, v4, v51, v50
	v_max3_f32 v4, v4, v52, v53
	v_max3_f32 v4, v4, v55, v54
	v_max3_f32 v4, v4, v56, v57
	v_max3_f32 v4, v4, v59, v58
	v_max3_f32 v4, v4, v60, v61
	v_max3_f32 v4, v4, v63, v62
	v_cndmask_b32_e64 v5, v113, v78, s[86:87]
	v_cndmask_b32_e64 v6, v113, v79, s[88:89]
	v_max3_f32 v4, v4, v5, v6
	v_cndmask_b32_e64 v78, v113, v80, s[90:91]
	v_cndmask_b32_e64 v79, v113, v81, s[92:93]
	v_max3_f32 v4, v4, v78, v79
	v_cndmask_b32_e64 v80, v113, v0, s[94:95]
	v_cndmask_b32_e64 v81, v113, v1, s[96:97]
	v_max3_f32 v0, v4, v80, v81
	v_cndmask_b32_e64 v85, v113, v2, s[4:5]
	v_cndmask_b32_e64 v86, v113, v3, s[0:1]
	v_max3_f32 v0, v0, v85, v86
	ds_swizzle_b32 v1, v0 offset:swizzle(SWAP,16)
	v_readlane_b32 s14, v253, 11
	v_bitop3_b32 v67, s16, v45, v26 bitop3:0x36
	v_bitop3_b32 v68, s16, v46, v26 bitop3:0x36
	v_bitop3_b32 v69, s16, v47, v26 bitop3:0x36
	s_waitcnt lgkmcnt(0)
; __device__ __forceinline__ unsigned cvt_pk_bf16(float lo, float hi) { unsigned r; asm volatile("v_cvt_pk_bf16_f32 %0, %1, %2" : "=v"(r) : "v"(lo), "v"(hi)); return r; }
; #define LAS __attribute__((address_space(3)))
; DI float sum_xor32(float v) { auto rr = __builtin_amdgcn_permlane32_swap(__float_as_uint(v), __float_as_uint(v), false, false); return __uint_as_float(rr[0]) + __uint_as_float(rr[1]); }
; DI float max_xor32(float v) { auto rr = __builtin_amdgcn_permlane32_swap(__float_as_uint(v), __float_as_uint(v), false, false); return fmaxf(__uint_as_float(rr[0]), __uint_as_float(rr[1])); }
; DI void phase_attn(const Ctx& C, bf16_t* Z, float* lse, bool dry) {
;     ...
;         mx = fmaxf(mx, lane_xor<16>(mx)); mx = max_xor32(mx);
;         float sum = 0.f;
; #pragma unroll
;         for (int x = 0; x < 10; ++x)
; #pragma unroll
;             for (int i = 0; i < 4; ++i) { const float p = __builtin_amdgcn_exp2f((st[x][i] - mx) * 1.4426950408889634f); st[x][i] = p; sum += p; }
;         sum += lane_xor<16>(sum); sum = sum_xor32(sum);
;         f32x4 o[4];
; #pragma unroll
;         for (int dt = 0; dt < 4; ++dt) o[dt] = (f32x4){0.f, 0.f, 0.f, 0.f};
; #pragma unroll
;         for (int y = 0; y < 5; ++y) {
;             u32x4 pw; pw.x = cvt_pk_bf16(st[2 * y][0], st[2 * y][1]); pw.y = cvt_pk_bf16(st[2 * y][2], st[2 * y][3]);
;             pw.z = cvt_pk_bf16(st[2 * y + 1][0], st[2 * y + 1][1]); pw.w = cvt_pk_bf16(st[2 * y + 1][2], st[2 * y + 1][3]);
;             const bf16x8 pb = __builtin_bit_cast(bf16x8, pw);
;             const int ka = 16 * ((t0 + 2 * y + rot16) & 15) + 4 * fq, kb = 16 * ((t0 + 2 * y + 1 + rot16) & 15) + 4 * fq;
; #pragma unroll
;             for (int dt = 0; dt < 4; ++dt) {
;                 const LAS bf16_t* vr = Vt + (16 * dt + fr) * 264; const int sw = ((2 * dt + (fr >> 3)) & 7) << 3;
;                 const s16x4 va = *(const LAS s16x4*)(vr + (ka ^ sw)), vb = *(const LAS s16x4*)(vr + (kb ^ sw));
;                 const bf16x8 a = {va[0], va[1], va[2], va[3], vb[0], vb[1], vb[2], vb[3]};
;                 o[dt] = __builtin_amdgcn_mfma_f32_16x16x32_bf16(a, pb, o[dt], 0, 0, 0);
	v_max_f32_e32 v1, v1, v1
	v_max_f32_e32 v0, v0, v1
	v_mov_b32_e32 v1, v0
	s_nop 1
	v_permlane32_swap_b32_e32 v0, v1
	v_max_f32_e32 v1, v1, v1
	v_max_f32_e32 v0, v0, v0
	v_max_f32_e32 v29, v0, v1
	v_sub_f32_e32 v3, v11, v29
	v_sub_f32_e32 v11, v16, v29
	v_mul_f32_e32 v11, 0x3fb8aa3b, v11
	v_exp_f32_e32 v87, v11
	v_sub_f32_e32 v11, v17, v29
	v_mul_f32_e32 v11, 0x3fb8aa3b, v11
	v_exp_f32_e32 v88, v11
	v_sub_f32_e32 v11, v18, v29
	v_mul_f32_e32 v11, 0x3fb8aa3b, v11
	v_exp_f32_e32 v89, v11
	v_sub_f32_e32 v11, v19, v29
	v_mul_f32_e32 v11, 0x3fb8aa3b, v11
	v_exp_f32_e32 v113, v11
	v_sub_f32_e32 v11, v20, v29
	v_mul_f32_e32 v11, 0x3fb8aa3b, v11
	v_exp_f32_e32 v114, v11
	v_sub_f32_e32 v11, v21, v29
	v_mul_f32_e32 v11, 0x3fb8aa3b, v11
	v_exp_f32_e32 v115, v11
	v_sub_f32_e32 v11, v22, v29
	v_mul_f32_e32 v11, 0x3fb8aa3b, v11
	v_exp_f32_e32 v116, v11
	v_sub_f32_e32 v11, v23, v29
	v_sub_f32_e32 v0, v8, v29
	v_mul_f32_e32 v11, 0x3fb8aa3b, v11
	v_mul_f32_e32 v0, 0x3fb8aa3b, v0
	v_sub_f32_e32 v1, v9, v29
	v_exp_f32_e32 v23, v11
	v_sub_f32_e32 v11, v48, v29
	v_exp_f32_e32 v0, v0
	v_mul_f32_e32 v1, 0x3fb8aa3b, v1
	v_sub_f32_e32 v2, v10, v29
	v_mul_f32_e32 v11, 0x3fb8aa3b, v11
	v_exp_f32_e32 v1, v1
	v_mul_f32_e32 v2, 0x3fb8aa3b, v2
	v_exp_f32_e32 v117, v11
	v_sub_f32_e32 v11, v49, v29
	v_exp_f32_e32 v2, v2
	v_mul_f32_e32 v3, 0x3fb8aa3b, v3
	v_sub_f32_e32 v7, v12, v29
	v_mul_f32_e32 v11, 0x3fb8aa3b, v11
	v_exp_f32_e32 v3, v3
	v_mul_f32_e32 v7, 0x3fb8aa3b, v7
	v_sub_f32_e32 v8, v13, v29
	v_exp_f32_e32 v119, v11
	v_sub_f32_e32 v11, v51, v29
	v_add_f32_e32 v4, 0, v0
	v_exp_f32_e32 v7, v7
	v_mul_f32_e32 v8, 0x3fb8aa3b, v8
	v_sub_f32_e32 v9, v14, v29
	v_mul_f32_e32 v11, 0x3fb8aa3b, v11
	v_add_f32_e32 v4, v1, v4
	v_exp_f32_e32 v8, v8
	v_mul_f32_e32 v9, 0x3fb8aa3b, v9
	v_sub_f32_e32 v10, v15, v29
	v_exp_f32_e32 v120, v11
	v_sub_f32_e32 v11, v50, v29
	v_add_f32_e32 v4, v2, v4
	v_exp_f32_e32 v9, v9
	v_mul_f32_e32 v10, 0x3fb8aa3b, v10
	v_mul_f32_e32 v11, 0x3fb8aa3b, v11
	v_add_f32_e32 v4, v3, v4
	v_exp_f32_e32 v10, v10
	v_exp_f32_e32 v121, v11
	v_sub_f32_e32 v11, v52, v29
	v_add_f32_e32 v4, v7, v4
	v_mul_f32_e32 v11, 0x3fb8aa3b, v11
	v_add_f32_e32 v4, v8, v4
	v_exp_f32_e32 v52, v11
	v_sub_f32_e32 v11, v53, v29
	v_add_f32_e32 v4, v9, v4
	v_mul_f32_e32 v11, 0x3fb8aa3b, v11
	v_add_f32_e32 v4, v10, v4
	v_exp_f32_e32 v53, v11
	v_sub_f32_e32 v11, v55, v29
	v_add_f32_e32 v4, v87, v4
	v_mul_f32_e32 v11, 0x3fb8aa3b, v11
	v_add_f32_e32 v4, v88, v4
	v_exp_f32_e32 v55, v11
	v_sub_f32_e32 v11, v54, v29
	v_add_f32_e32 v4, v89, v4
	v_mul_f32_e32 v11, 0x3fb8aa3b, v11
	v_add_f32_e32 v4, v113, v4
	v_exp_f32_e32 v54, v11
	v_sub_f32_e32 v11, v56, v29
	v_add_f32_e32 v4, v114, v4
	v_mul_f32_e32 v11, 0x3fb8aa3b, v11
	v_add_f32_e32 v4, v115, v4
	v_exp_f32_e32 v56, v11
	v_sub_f32_e32 v11, v57, v29
	v_add_f32_e32 v4, v116, v4
	v_mul_f32_e32 v11, 0x3fb8aa3b, v11
	v_add_f32_e32 v4, v23, v4
	v_exp_f32_e32 v57, v11
	v_sub_f32_e32 v11, v59, v29
	v_add_f32_e32 v4, v117, v4
	v_mul_f32_e32 v11, 0x3fb8aa3b, v11
	v_add_f32_e32 v4, v119, v4
	v_exp_f32_e32 v59, v11
	v_sub_f32_e32 v11, v58, v29
	v_add_f32_e32 v4, v120, v4
	v_mul_f32_e32 v11, 0x3fb8aa3b, v11
	v_add_f32_e32 v4, v121, v4
	v_exp_f32_e32 v58, v11
	v_sub_f32_e32 v11, v60, v29
	v_add_f32_e32 v4, v52, v4
	v_mul_f32_e32 v11, 0x3fb8aa3b, v11
	v_add_f32_e32 v4, v53, v4
	v_exp_f32_e32 v60, v11
	v_sub_f32_e32 v11, v61, v29
	v_add_f32_e32 v4, v55, v4
	v_mul_f32_e32 v11, 0x3fb8aa3b, v11
	v_add_f32_e32 v4, v54, v4
	v_exp_f32_e32 v61, v11
	v_sub_f32_e32 v11, v63, v29
	v_add_f32_e32 v4, v56, v4
	v_mul_f32_e32 v11, 0x3fb8aa3b, v11
	v_add_f32_e32 v4, v57, v4
	v_exp_f32_e32 v63, v11
	v_sub_f32_e32 v11, v62, v29
	v_add_f32_e32 v4, v59, v4
	v_mul_f32_e32 v11, 0x3fb8aa3b, v11
	v_add_f32_e32 v4, v58, v4
	v_exp_f32_e32 v62, v11
	v_add_f32_e32 v4, v60, v4
	v_add_f32_e32 v4, v61, v4
	v_add_f32_e32 v4, v63, v4
	v_add_f32_e32 v16, v62, v4
	v_sub_f32_e32 v4, v5, v29
	v_mul_f32_e32 v4, 0x3fb8aa3b, v4
	v_exp_f32_e32 v122, v4
	v_sub_f32_e32 v4, v6, v29
	v_mul_f32_e32 v11, 0x3fb8aa3b, v4
	v_cvt_pk_bf16_f32 v0, v0, v1
	v_cvt_pk_bf16_f32 v1, v2, v3
	v_cvt_pk_bf16_f32 v2, v7, v8
	v_sub_f32_e32 v8, v78, v29
	v_lshl_add_u32 v4, v66, 1, v44
	v_exp_f32_e32 v66, v11
	v_mul_f32_e32 v8, 0x3fb8aa3b, v8
	v_lshl_add_u32 v6, v73, 1, v44
	v_exp_f32_e32 v73, v8
	v_add_f32_e32 v16, v122, v16
	v_bitop3_b32 v71, s3, v45, v26 bitop3:0x36
	v_bitop3_b32 v70, s3, v46, v26 bitop3:0x36
	v_bitop3_b32 v72, s3, v47, v26 bitop3:0x36
	s_add_i32 s3, s13, s14
	v_add_f32_e32 v16, v66, v16
	s_lshl_b32 s3, s3, 4
	v_cvt_pk_bf16_f32 v3, v9, v10
	v_lshl_add_u32 v8, v67, 1, v44
	v_lshl_add_u32 v10, v71, 1, v44
	v_lshl_add_u32 v12, v68, 1, v44
	v_lshl_add_u32 v14, v70, 1, v44
	v_add_f32_e32 v67, v73, v16
	v_lshl_add_u32 v16, v69, 1, v44
	v_lshl_add_u32 v18, v72, 1, v44
	s_and_b32 s3, s3, 0xf0
	ds_read_b64 v[4:5], v4 offset:36864
	ds_read_b64 v[6:7], v6 offset:36864
	ds_read_b64 v[8:9], v8 offset:45312
	ds_read_b64 v[10:11], v10 offset:45312
	ds_read_b64 v[12:13], v12 offset:53760
	ds_read_b64 v[14:15], v14 offset:53760
	ds_read_b64 v[16:17], v16 offset:62208
	ds_read_b64 v[18:19], v18 offset:62208
	v_bitop3_b32 v74, s3, v39, v26 bitop3:0x36
	v_bitop3_b32 v75, s3, v45, v26 bitop3:0x36
	v_bitop3_b32 v76, s3, v46, v26 bitop3:0x36
	v_bitop3_b32 v77, s3, v47, v26 bitop3:0x36
	s_add_i32 s3, s2, s14
	s_lshl_b32 s3, s3, 4
	s_and_b32 s3, s3, 0xf0
	v_bitop3_b32 v90, s3, v39, v26 bitop3:0x36
	v_bitop3_b32 v91, s3, v45, v26 bitop3:0x36
	s_waitcnt lgkmcnt(6)
	v_mfma_f32_16x16x32_bf16 v[4:7], v[4:7], v[0:3], 0
	v_lshl_add_u32 v48, v74, 1, v44
	v_lshl_add_u32 v50, v90, 1, v44
	v_cvt_pk_bf16_f32 v20, v87, v88
	s_waitcnt lgkmcnt(4)
; __device__ __forceinline__ unsigned cvt_pk_bf16(float lo, float hi) { unsigned r; asm volatile("v_cvt_pk_bf16_f32 %0, %1, %2" : "=v"(r) : "v"(lo), "v"(hi)); return r; }
; #define LAS __attribute__((address_space(3)))
; DI void phase_attn(const Ctx& C, bf16_t* Z, float* lse, bool dry) {
;     ...
; #pragma unroll
;         for (int y = 0; y < 5; ++y) {
;             u32x4 pw; pw.x = cvt_pk_bf16(st[2 * y][0], st[2 * y][1]); pw.y = cvt_pk_bf16(st[2 * y][2], st[2 * y][3]);
;             pw.z = cvt_pk_bf16(st[2 * y + 1][0], st[2 * y + 1][1]); pw.w = cvt_pk_bf16(st[2 * y + 1][2], st[2 * y + 1][3]);
;             const bf16x8 pb = __builtin_bit_cast(bf16x8, pw);
;             const int ka = 16 * ((t0 + 2 * y + rot16) & 15) + 4 * fq, kb = 16 * ((t0 + 2 * y + 1 + rot16) & 15) + 4 * fq;
; #pragma unroll
;             for (int dt = 0; dt < 4; ++dt) {
;                 const LAS bf16_t* vr = Vt + (16 * dt + fr) * 264; const int sw = ((2 * dt + (fr >> 3)) & 7) << 3;
;                 const s16x4 va = *(const LAS s16x4*)(vr + (ka ^ sw)), vb = *(const LAS s16x4*)(vr + (kb ^ sw));
;                 const bf16x8 a = {va[0], va[1], va[2], va[3], vb[0], vb[1], vb[2], vb[3]};
;                 o[dt] = __builtin_amdgcn_mfma_f32_16x16x32_bf16(a, pb, o[dt], 0, 0, 0);
;             }
	v_mfma_f32_16x16x32_bf16 v[8:11], v[8:11], v[0:3], 0
	v_cvt_pk_bf16_f32 v21, v89, v113
	v_cvt_pk_bf16_f32 v22, v114, v115
	v_cvt_pk_bf16_f32 v23, v116, v23
	s_waitcnt lgkmcnt(2)
	v_mfma_f32_16x16x32_bf16 v[12:15], v[12:15], v[0:3], 0
	ds_read_b64 v[48:49], v48 offset:36864
	ds_read_b64 v[50:51], v50 offset:36864
	v_readlane_b32 s14, v253, 18
	v_bitop3_b32 v92, s3, v46, v26 bitop3:0x36
	s_waitcnt lgkmcnt(2)
	v_mfma_f32_16x16x32_bf16 v[0:3], v[16:19], v[0:3], 0
	v_lshl_add_u32 v16, v75, 1, v44
	v_lshl_add_u32 v18, v91, 1, v44
	ds_read_b64 v[16:17], v16 offset:45312
	ds_read_b64 v[18:19], v18 offset:45312
	v_bitop3_b32 v93, s3, v47, v26 bitop3:0x36
	s_add_i32 s3, s13, s14
	s_lshl_b32 s3, s3, 4
	s_waitcnt lgkmcnt(2)
	v_mfma_f32_16x16x32_bf16 v[4:7], v[48:51], v[20:23], v[4:7]
	v_lshl_add_u32 v48, v76, 1, v44
	v_lshl_add_u32 v50, v92, 1, v44
	s_and_b32 s3, s3, 0xf0
	s_waitcnt lgkmcnt(0)
	v_mfma_f32_16x16x32_bf16 v[8:11], v[16:19], v[20:23], v[8:11]
	v_lshl_add_u32 v16, v77, 1, v44
	v_lshl_add_u32 v18, v93, 1, v44
	ds_read_b64 v[48:49], v48 offset:53760
	ds_read_b64 v[50:51], v50 offset:53760
	ds_read_b64 v[16:17], v16 offset:62208
	ds_read_b64 v[18:19], v18 offset:62208
	v_bitop3_b32 v94, s3, v39, v26 bitop3:0x36
	v_bitop3_b32 v95, s3, v45, v26 bitop3:0x36
	v_bitop3_b32 v96, s3, v46, v26 bitop3:0x36
	v_bitop3_b32 v97, s3, v47, v26 bitop3:0x36
	s_add_i32 s3, s2, s14
	s_lshl_b32 s3, s3, 4
	s_and_b32 s3, s3, 0xf0
	v_bitop3_b32 v98, s3, v39, v26 bitop3:0x36
	v_bitop3_b32 v99, s3, v45, v26 bitop3:0x36
	s_waitcnt lgkmcnt(2)
	v_mfma_f32_16x16x32_bf16 v[12:15], v[48:51], v[20:23], v[12:15]
	v_cvt_pk_bf16_f32 v48, v117, v119
	v_cvt_pk_bf16_f32 v49, v120, v121
	v_cvt_pk_bf16_f32 v50, v52, v53
	v_cvt_pk_bf16_f32 v51, v55, v54
	v_lshl_add_u32 v52, v94, 1, v44
	v_lshl_add_u32 v54, v98, 1, v44
	s_waitcnt lgkmcnt(0)
	v_mfma_f32_16x16x32_bf16 v[0:3], v[16:19], v[20:23], v[0:3]
	v_lshl_add_u32 v16, v95, 1, v44
	v_lshl_add_u32 v18, v99, 1, v44
	ds_read_b64 v[52:53], v52 offset:36864
	ds_read_b64 v[54:55], v54 offset:36864
	ds_read_b64 v[16:17], v16 offset:45312
	ds_read_b64 v[18:19], v18 offset:45312
	v_readlane_b32 s14, v253, 25
	v_bitop3_b32 v100, s3, v46, v26 bitop3:0x36
	v_bitop3_b32 v101, s3, v47, v26 bitop3:0x36
	s_add_i32 s3, s13, s14
	s_lshl_b32 s3, s3, 4
	v_lshl_add_u32 v20, v96, 1, v44
	v_lshl_add_u32 v22, v100, 1, v44
	s_waitcnt lgkmcnt(0)
	v_mfma_f32_16x16x32_bf16 v[8:11], v[16:19], v[48:51], v[8:11]
	v_lshl_add_u32 v16, v97, 1, v44
	v_lshl_add_u32 v18, v101, 1, v44
	s_and_b32 s3, s3, 0xf0
	ds_read_b64 v[20:21], v20 offset:53760
	ds_read_b64 v[22:23], v22 offset:53760
	ds_read_b64 v[16:17], v16 offset:62208
	ds_read_b64 v[18:19], v18 offset:62208
	v_bitop3_b32 v102, s3, v39, v26 bitop3:0x36
	v_bitop3_b32 v103, s3, v45, v26 bitop3:0x36
	v_bitop3_b32 v104, s3, v46, v26 bitop3:0x36
	v_bitop3_b32 v105, s3, v47, v26 bitop3:0x36
	s_add_i32 s3, s2, s14
	s_lshl_b32 s3, s3, 4
	s_and_b32 s3, s3, 0xf0
	v_sub_f32_e32 v70, v81, v29
	v_bitop3_b32 v106, s3, v39, v26 bitop3:0x36
	v_bitop3_b32 v107, s3, v45, v26 bitop3:0x36
	v_mfma_f32_16x16x32_bf16 v[4:7], v[52:55], v[48:51], v[4:7]
	v_mul_f32_e32 v52, 0x3fb8aa3b, v70
	v_exp_f32_e32 v70, v52
	v_lshl_add_u32 v52, v102, 1, v44
	v_lshl_add_u32 v54, v106, 1, v44
	s_waitcnt lgkmcnt(0)
	v_mfma_f32_16x16x32_bf16 v[0:3], v[16:19], v[48:51], v[0:3]
	v_lshl_add_u32 v16, v103, 1, v44
	v_lshl_add_u32 v18, v107, 1, v44
	v_sub_f32_e32 v68, v79, v29
	v_mfma_f32_16x16x32_bf16 v[12:15], v[20:23], v[48:51], v[12:15]
	v_cvt_pk_bf16_f32 v20, v56, v57
	v_cvt_pk_bf16_f32 v21, v59, v58
	v_cvt_pk_bf16_f32 v22, v60, v61
	v_cvt_pk_bf16_f32 v23, v63, v62
	ds_read_b64 v[52:53], v52 offset:36864
	ds_read_b64 v[54:55], v54 offset:36864
	ds_read_b64 v[16:17], v16 offset:45312
	ds_read_b64 v[18:19], v18 offset:45312
	v_mul_f32_e32 v68, 0x3fb8aa3b, v68
	v_sub_f32_e32 v69, v80, v29
	v_exp_f32_e32 v68, v68
	v_mul_f32_e32 v69, 0x3fb8aa3b, v69
	v_bitop3_b32 v108, s3, v46, v26 bitop3:0x36
	v_exp_f32_e32 v69, v69
	v_sub_f32_e32 v71, v85, v29
	v_mul_f32_e32 v56, 0x3fb8aa3b, v71
	v_sub_f32_e32 v61, v86, v29
	v_lshl_add_u32 v48, v104, 1, v44
	v_lshl_add_u32 v50, v108, 1, v44
	v_exp_f32_e32 v60, v56
	ds_read_b64 v[48:49], v48 offset:53760
	ds_read_b64 v[50:51], v50 offset:53760
	s_waitcnt lgkmcnt(2)
; __device__ __forceinline__ unsigned cvt_pk_bf16(float lo, float hi) { unsigned r; asm volatile("v_cvt_pk_bf16_f32 %0, %1, %2" : "=v"(r) : "v"(lo), "v"(hi)); return r; }
; #define LAS __attribute__((address_space(3)))
; #define GAS __attribute__((address_space(1)))
; DI float sum_xor32(float v) { auto rr = __builtin_amdgcn_permlane32_swap(__float_as_uint(v), __float_as_uint(v), false, false); return __uint_as_float(rr[0]) + __uint_as_float(rr[1]); }
; DI void phase_attn(const Ctx& C, bf16_t* Z, float* lse, bool dry) {
;     ...
;         sum += lane_xor<16>(sum); sum = sum_xor32(sum);
;         f32x4 o[4];
; #pragma unroll
;         for (int dt = 0; dt < 4; ++dt) o[dt] = (f32x4){0.f, 0.f, 0.f, 0.f};
; #pragma unroll
;         for (int y = 0; y < 5; ++y) {
;             u32x4 pw; pw.x = cvt_pk_bf16(st[2 * y][0], st[2 * y][1]); pw.y = cvt_pk_bf16(st[2 * y][2], st[2 * y][3]);
;             pw.z = cvt_pk_bf16(st[2 * y + 1][0], st[2 * y + 1][1]); pw.w = cvt_pk_bf16(st[2 * y + 1][2], st[2 * y + 1][3]);
;             const bf16x8 pb = __builtin_bit_cast(bf16x8, pw);
;             const int ka = 16 * ((t0 + 2 * y + rot16) & 15) + 4 * fq, kb = 16 * ((t0 + 2 * y + 1 + rot16) & 15) + 4 * fq;
; #pragma unroll
;             for (int dt = 0; dt < 4; ++dt) {
;                 const LAS bf16_t* vr = Vt + (16 * dt + fr) * 264; const int sw = ((2 * dt + (fr >> 3)) & 7) << 3;
;                 const s16x4 va = *(const LAS s16x4*)(vr + (ka ^ sw)), vb = *(const LAS s16x4*)(vr + (kb ^ sw));
;                 const bf16x8 a = {va[0], va[1], va[2], va[3], vb[0], vb[1], vb[2], vb[3]};
;                 o[dt] = __builtin_amdgcn_mfma_f32_16x16x32_bf16(a, pb, o[dt], 0, 0, 0);
;             }
;         }
;         const float inv = 1.0f / sum;
;         bf16_t* qst = dry ? (bf16_t*)(C.ws + WS_PP) + tid * 64 : qp;
; #pragma unroll
;         for (int dt = 0; dt < 4; ++dt) {
;             u32x2 wv; wv.x = cvt_pk_bf16(o[dt][0] * inv, o[dt][1] * inv); wv.y = cvt_pk_bf16(o[dt][2] * inv, o[dt][3] * inv);
;             *(GAS u32x2*)(qst + 16 * dt + 4 * fq) = wv;
;         }
;         if (fq == 0) *(GAS float*)(dry ? (float*)(C.ws + WS_PP) + 1048576 + tid : lse + qrow * 12 + head) = mx + __builtin_amdgcn_logf(sum) * 0.6931471805599453f;
;         __syncthreads();
	v_mfma_f32_16x16x32_bf16 v[56:59], v[16:19], v[20:23], v[8:11]
	v_bitop3_b32 v109, s3, v47, v26 bitop3:0x36
	v_add_f32_e32 v67, v68, v67
	v_add_f32_e32 v67, v69, v67
	v_mul_f32_e32 v8, 0x3fb8aa3b, v61
	v_exp_f32_e32 v61, v8
	v_mfma_f32_16x16x32_bf16 v[4:7], v[52:55], v[20:23], v[4:7]
	v_lshl_add_u32 v52, v105, 1, v44
	v_lshl_add_u32 v54, v109, 1, v44
	v_readlane_b32 s14, v253, 33
	ds_read_b64 v[52:53], v52 offset:62208
	ds_read_b64 v[54:55], v54 offset:62208
	v_add_f32_e32 v8, v70, v67
	s_add_i32 s13, s13, s14
	s_add_i32 s2, s2, s14
	v_add_f32_e32 v8, v60, v8
	s_lshl_b32 s3, s13, 4
	s_lshl_b32 s2, s2, 4
	s_waitcnt lgkmcnt(2)
	v_mfma_f32_16x16x32_bf16 v[16:19], v[48:51], v[20:23], v[12:15]
	v_add_f32_e32 v48, v61, v8
	s_and_b32 s3, s3, 0xf0
	s_and_b32 s2, s2, 0xf0
	ds_swizzle_b32 v49, v48 offset:swizzle(SWAP,16)
	v_bitop3_b32 v65, s3, v39, v26 bitop3:0x36
	v_bitop3_b32 v110, s3, v45, v26 bitop3:0x36
	v_bitop3_b32 v82, s2, v39, v26 bitop3:0x36
	v_bitop3_b32 v83, s2, v45, v26 bitop3:0x36
	s_waitcnt lgkmcnt(1)
	v_mfma_f32_16x16x32_bf16 v[8:11], v[52:55], v[20:23], v[0:3]
	v_lshl_add_u32 v20, v110, 1, v44
	v_lshl_add_u32 v22, v83, 1, v44
	v_cvt_pk_bf16_f32 v12, v122, v66
	v_cvt_pk_bf16_f32 v13, v73, v68
	v_cvt_pk_bf16_f32 v14, v69, v70
	s_nop 0
	v_lshl_add_u32 v0, v65, 1, v44
	v_lshl_add_u32 v2, v82, 1, v44
	v_cvt_pk_bf16_f32 v15, v60, v61
	ds_read_b64 v[0:1], v0 offset:36864
	ds_read_b64 v[2:3], v2 offset:36864
	ds_read_b64 v[20:21], v20 offset:45312
	ds_read_b64 v[22:23], v22 offset:45312
	s_waitcnt lgkmcnt(4)
	v_add_f32_e32 v48, v48, v49
	v_mov_b32_e32 v49, v48
	v_bitop3_b32 v111, s3, v46, v26 bitop3:0x36
	v_bitop3_b32 v84, s2, v46, v26 bitop3:0x36
	v_permlane32_swap_b32_e32 v48, v49
	s_waitcnt lgkmcnt(2)
	v_mfma_f32_16x16x32_bf16 v[4:7], v[0:3], v[12:15], v[4:7]
	v_add_f32_e32 v48, v48, v49
	v_bitop3_b32 v112, s3, v47, v26 bitop3:0x36
	v_bitop3_b32 v64, s2, v47, v26 bitop3:0x36
	s_waitcnt lgkmcnt(0)
	v_mfma_f32_16x16x32_bf16 v[0:3], v[20:23], v[12:15], v[56:59]
	v_lshl_add_u32 v20, v111, 1, v44
	v_lshl_add_u32 v22, v84, 1, v44
	ds_read_b64 v[20:21], v20 offset:53760
	ds_read_b64 v[22:23], v22 offset:53760
	v_div_scale_f32 v49, s[2:3], v48, v48, 1.0
	v_rcp_f32_e32 v56, v49
	s_waitcnt lgkmcnt(0)
	v_mfma_f32_16x16x32_bf16 v[16:19], v[20:23], v[12:15], v[16:19]
	v_lshl_add_u32 v50, v112, 1, v44
	v_fma_f32 v20, -v49, v56, 1.0
	v_fmac_f32_e32 v56, v20, v56
	v_div_scale_f32 v20, vcc, 1.0, v48, 1.0
	v_lshl_add_u32 v51, v64, 1, v44
	ds_read_b64 v[52:53], v50 offset:62208
	ds_read_b64 v[54:55], v51 offset:62208
	v_mul_f32_e32 v21, v20, v56
	v_fma_f32 v22, -v49, v21, v20
	v_fmac_f32_e32 v21, v22, v56
	v_fma_f32 v20, -v49, v21, v20
	v_div_fmas_f32 v20, v20, v56, v21
	s_waitcnt lgkmcnt(0)
	v_mfma_f32_16x16x32_bf16 v[8:11], v[52:55], v[12:15], v[8:11]
	v_div_fixup_f32 v14, v20, v48, 1.0
	v_mul_f32_e32 v4, v14, v4
	v_mul_f32_e32 v5, v14, v5
	v_lshl_add_u64 v[12:13], v[32:33], 0, v[192:193]
	v_cvt_pk_bf16_f32 v4, v4, v5
	v_mul_f32_e32 v5, v14, v6
	v_mul_f32_e32 v0, v14, v0
	v_mul_f32_e32 v1, v14, v1
	v_mul_f32_e32 v6, v14, v7
	v_cvt_pk_bf16_f32 v5, v5, v6
	global_store_dwordx2 v[12:13], v[4:5], off
	v_cvt_pk_bf16_f32 v0, v0, v1
	v_mul_f32_e32 v1, v14, v2
	v_mul_f32_e32 v2, v14, v3
	v_cvt_pk_bf16_f32 v1, v1, v2
	global_store_dwordx2 v[12:13], v[0:1], off offset:32
	v_mul_f32_e32 v0, v14, v16
	v_mul_f32_e32 v1, v14, v17
	v_cvt_pk_bf16_f32 v0, v0, v1
	v_mul_f32_e32 v1, v14, v18
	v_mul_f32_e32 v2, v14, v19
	v_cvt_pk_bf16_f32 v1, v1, v2
	global_store_dwordx2 v[12:13], v[0:1], off offset:64
	v_mul_f32_e32 v0, v14, v8
	v_mul_f32_e32 v1, v14, v9
	v_cvt_pk_bf16_f32 v0, v0, v1
	v_mul_f32_e32 v1, v14, v10
	v_mul_f32_e32 v2, v14, v11
	v_cvt_pk_bf16_f32 v1, v1, v2
	global_store_dwordx2 v[12:13], v[0:1], off offset:96
	s_and_saveexec_b64 s[14:15], s[30:31]
	s_cbranch_execz .LBB0_204
	v_log_f32_e32 v3, v48
	v_mad_u64_u32 v[0:1], s[2:3], v30, 48, s[28:29]
	v_mov_b32_e32 v2, v1
	v_fmac_f32_e32 v29, 0x3f317218, v3
	v_mad_u64_u32 v[2:3], s[2:3], v31, 48, v[2:3]
	v_mov_b32_e32 v1, v2
	s_ashr_i32 s13, s12, 31
	v_lshl_add_u64 v[0:1], s[12:13], 2, v[0:1]
	global_store_dword v[0:1], v29, off
	s_branch .LBB0_204

; #define PG8_STAGE(bufoff, gbase, voff) do { _Pragma("unroll") for (int _i = 0; _i < 2; ++_i) \
;         __builtin_amdgcn_global_load_lds((const unsigned*)((const char*)(gbase) + (voff)[_i]), (PG8_LAS unsigned*)(lds + (bufoff) + ldsw + _i * 8192), 16, 0, 0); } while (0)
; #define PG8_WAIT_V(n) asm volatile("s_waitcnt vmcnt(" #n ")" ::: "memory")
; #define PG8_BAR __builtin_amdgcn_s_barrier()
; template <class Epi, class Sched, bool ALIGN_EPI = false, bool SP2 = false>
; __device__ __forceinline__ void gemm_phase(PG8_LAS unsigned char* lds, const Gemm g, const Sched& S, const Epi& E) {
;     ...
;     for (int i = 0; i < 2; ++i) { int R, C; stage_rc(tid * 16 + i * 8192, R, C); const int Rb = Epi::PERM ? ((R & ~31) + perm32(R & 31)) : R;
;         voffA[i] = (unsigned)(R * g.lda + C) * 2u; voffB[i] = (unsigned)(Rb * g.ldb + C) * 2u; }
;     const size_t kstep = (size_t)(BK * 2);
;     const size_t hstepA = (size_t)HALF * g.lda * 2, hstepB = (size_t)HALF * g.ldb * 2;
;     const size_t tstepA = 2 * hstepA, tstepB = 2 * hstepB;
;     const unsigned ldsw = (unsigned)wid * 1024u;
;     const int aoff = lds_byte(wr * 64 + fr, fq * 8), boff = lds_byte(wc * 32 + fr, fq * 8);
;     ...
;         PG8_STAGE(PG8_SB(0, 0), cB, voffB); PG8_STAGE(PG8_SB(0, 1), cB + hstepB, voffB); PG8_STAGE(PG8_SA(0, 0), cA, voffA); PG8_STAGE(PG8_SA(0, 1), cA + hstepA, voffA);
;         if (wr == 1) PG8_BAR;
;         PG8_WAIT_V(2); PG8_BAR;
;         PG8_STAGE(PG8_SB(1, 0), cB + kstep, voffB); PG8_STAGE(PG8_SA(1, 0), cA + kstep, voffA); PG8_STAGE(PG8_SB(1, 1), cB + hstepB + kstep, voffB);
;         PG8_WAIT_V(6); PG8_BAR;
.LBB0_624:
	v_readlane_b32 s6, v254, 61
	s_and_b32 s62, s1, 3
	s_lshl_b32 s63, s2, 6
	v_and_b32_e32 v7, 48, v6
	s_lshl_b32 s1, s2, 13
	v_lshlrev_b32_e32 v16, 6, v6
	s_movk_i32 s2, 0x3c0
	v_lshlrev_b32_e32 v6, 2, v6
	v_readlane_b32 s7, v254, 62
	v_and_or_b32 v7, v16, s2, v7
	v_and_b32_e32 v6, 32, v6
	v_lshl_add_u64 v[8:9], s[6:7], 0, v[192:193]
	v_mov_b32_e32 v177, v193
	v_readlane_b32 s4, v254, 57
	v_bitop3_b32 v16, v7, s1, v6 bitop3:0xde
	s_lshl_b32 s1, s62, 12
	v_lshl_add_u64 v[10:11], s[6:7], 0, v[176:177]
	v_mov_b32_e32 v181, v193
	v_readlane_b32 s5, v254, 58
	v_bitop3_b32 v230, v7, s1, v6 bitop3:0xde
	s_add_i32 m0, s20, 0x18000
	v_lshl_add_u64 v[6:7], v[8:9], 0, s[36:37]
	v_lshl_add_u64 v[12:13], s[4:5], 0, v[180:181]
	v_mov_b32_e32 v179, v193
	global_load_lds_dwordx4 v[6:7], off
	v_lshl_add_u64 v[6:7], v[10:11], 0, s[36:37]
	s_add_i32 m0, s20, 0x1a000
	s_add_i32 s65, s20, 0x8000
	v_lshl_add_u64 v[14:15], s[4:5], 0, v[178:179]
	global_load_lds_dwordx4 v[6:7], off
	v_lshl_add_u64 v[6:7], v[12:13], 0, s[36:37]
	s_mov_b32 m0, s65
	s_add_i32 s80, s20, 0xa000
	v_readlane_b32 s2, v254, 63
	global_load_lds_dwordx4 v[6:7], off
	v_lshl_add_u64 v[6:7], v[14:15], 0, s[36:37]
	s_mov_b32 m0, s80
	v_readlane_b32 s3, v255, 0
	global_load_lds_dwordx4 v[6:7], off
	s_add_i32 m0, s20, 0x1c000
	v_lshl_add_u64 v[6:7], s[2:3], 0, v[192:193]
	global_load_lds_dwordx4 v[6:7], off
	v_lshl_add_u64 v[6:7], s[2:3], 0, v[176:177]
	s_add_i32 m0, s20, 0x1e000
	s_lshl_b32 s64, s62, 5
	global_load_lds_dwordx4 v[6:7], off
	s_waitcnt vmcnt(8)
	s_barrier
	v_lshlrev_b32_e32 v6, 14, v0
	v_and_b32_e32 v6, 0xffff8000, v6
	s_cmpk_lt_u32 s0, 0x100
	v_lshl_add_u32 v1, v1, 11, v6
	v_and_b32_e32 v0, 1, v0
	s_cselect_b64 s[12:13], -1, 0
	s_lshl_b32 s0, s62, 6
	v_lshl_or_b32 v0, v0, 6, v1
	s_add_u32 s88, s58, s0
	v_lshl_add_u32 v182, v2, 1, v0
	v_lshlrev_b32_e32 v0, 14, v4
	s_addc_u32 s89, s59, 0
	v_and_b32_e32 v0, 0xffff8000, v0
	s_waitcnt vmcnt(6)
	s_add_u32 s90, s28, s0
	v_lshl_add_u32 v0, v3, 11, v0
	v_and_b32_e32 v1, 1, v4
	v_readlane_b32 s0, v254, 1
	v_lshl_or_b32 v0, v1, 6, v0
	v_readlane_b32 s1, v254, 2
	s_addc_u32 s91, s29, 0
	v_mov_b32_e32 v183, v193
	v_lshl_add_u32 v184, v5, 1, v0
	v_mov_b32_e32 v185, v193
	s_mov_b32 s92, 0
	v_add_u32_e32 v231, 0, v16
	v_readlane_b32 s34, v254, 16
	s_mov_b32 s86, s0
	s_mov_b64 s[0:1], s[4:5]
	s_barrier
	s_branch .LBB0_627

; #define PG8_STAGE(bufoff, gbase, voff) do { _Pragma("unroll") for (int _i = 0; _i < 2; ++_i) \
;         __builtin_amdgcn_global_load_lds((const unsigned*)((const char*)(gbase) + (voff)[_i]), (PG8_LAS unsigned*)(lds + (bufoff) + ldsw + _i * 8192), 16, 0, 0); } while (0)
; #define PG8_WAIT_V(n) asm volatile("s_waitcnt vmcnt(" #n ")" ::: "memory")
; #define PG8_BAR __builtin_amdgcn_s_barrier()
; template <class Epi, class Sched, bool ALIGN_EPI = false, bool SP2 = false>
; __device__ __forceinline__ void gemm_phase(PG8_LAS unsigned char* lds, const Gemm g, const Sched& S, const Epi& E) {
;     ...
;     for (int i = 0; i < 2; ++i) { int R, C; stage_rc(tid * 16 + i * 8192, R, C); const int Rb = Epi::PERM ? ((R & ~31) + perm32(R & 31)) : R;
;         voffA[i] = (unsigned)(R * g.lda + C) * 2u; voffB[i] = (unsigned)(Rb * g.ldb + C) * 2u; }
;     const size_t kstep = (size_t)(BK * 2);
;     const size_t hstepA = (size_t)HALF * g.lda * 2, hstepB = (size_t)HALF * g.ldb * 2;
;     const size_t tstepA = 2 * hstepA, tstepB = 2 * hstepB;
;     const unsigned ldsw = (unsigned)wid * 1024u;
;     const int aoff = lds_byte(wr * 64 + fr, fq * 8), boff = lds_byte(wc * 32 + fr, fq * 8);
;     ...
;         PG8_STAGE(PG8_SB(0, 0), cB, voffB); PG8_STAGE(PG8_SB(0, 1), cB + hstepB, voffB); PG8_STAGE(PG8_SA(0, 0), cA, voffA); PG8_STAGE(PG8_SA(0, 1), cA + hstepA, voffA);
;         if (wr == 1) PG8_BAR;
;         PG8_WAIT_V(2); PG8_BAR;
;         PG8_STAGE(PG8_SB(1, 0), cB + kstep, voffB); PG8_STAGE(PG8_SA(1, 0), cA + kstep, voffA); PG8_STAGE(PG8_SB(1, 1), cB + hstepB + kstep, voffB);
;         PG8_WAIT_V(6); PG8_BAR;
.LBB0_662:
	v_readlane_b32 s88, v254, 44
	s_lshl_b32 s1, s1, 5
	v_readlane_b32 s89, v254, 45
	v_and_b32_e32 v1, 48, v0
	v_lshlrev_b32_e32 v10, 6, v0
	s_movk_i32 s3, 0x3c0
	v_lshlrev_b32_e32 v0, 2, v0
	s_and_b32 s62, s1, 0x60
	v_lshl_add_u64 v[2:3], s[88:89], 0, v[192:193]
	v_mov_b32_e32 v129, v193
	v_readlane_b32 s86, v254, 40
	s_lshl_b32 s49, s2, 6
	s_lshl_b32 s2, s2, 13
	v_and_or_b32 v1, v10, s3, v1
	v_and_b32_e32 v0, 32, v0
	s_lshl_b32 s1, s62, 7
	v_lshl_add_u64 v[4:5], s[88:89], 0, v[128:129]
	v_mov_b32_e32 v133, v193
	v_readlane_b32 s87, v254, 41
	v_bitop3_b32 v10, v1, s2, v0 bitop3:0xde
	v_bitop3_b32 v136, s1, v1, v0 bitop3:0xf6
	s_add_i32 m0, s20, 0x18000
	v_lshl_add_u64 v[0:1], v[2:3], 0, s[36:37]
	v_lshl_add_u64 v[6:7], s[86:87], 0, v[132:133]
	v_mov_b32_e32 v131, v193
	global_load_lds_dwordx4 v[0:1], off
	v_lshl_add_u64 v[0:1], v[4:5], 0, s[36:37]
	s_add_i32 m0, s20, 0x1a000
	s_add_i32 s63, s20, 0x8000
	v_lshl_add_u64 v[8:9], s[86:87], 0, v[130:131]
	global_load_lds_dwordx4 v[0:1], off
	v_lshl_add_u64 v[0:1], v[6:7], 0, s[36:37]
	s_mov_b32 m0, s63
	s_add_i32 s64, s20, 0xa000
	v_readlane_b32 s2, v254, 46
	global_load_lds_dwordx4 v[0:1], off
	v_lshl_add_u64 v[0:1], v[8:9], 0, s[36:37]
	s_mov_b32 m0, s64
	v_readlane_b32 s3, v254, 47
	global_load_lds_dwordx4 v[0:1], off
	s_add_i32 m0, s20, 0x1c000
	v_lshl_add_u64 v[0:1], s[2:3], 0, v[192:193]
	global_load_lds_dwordx4 v[0:1], off
	v_lshl_add_u64 v[0:1], s[2:3], 0, v[128:129]
	s_add_i32 m0, s20, 0x1e000
	s_cmpk_lt_u32 s0, 0x100
	global_load_lds_dwordx4 v[0:1], off
	s_waitcnt vmcnt(8)
	s_barrier
	s_waitcnt vmcnt(6)
	v_readlane_b32 s10, v255, 1
	v_readlane_b32 s0, v254, 1
	s_cselect_b64 s[6:7], -1, 0
	v_add_u32_e32 v137, 0, v10
	v_readlane_b32 s11, v255, 2
	v_readlane_b32 s65, v254, 16
	s_mov_b32 s78, s0
	s_barrier
	v_readlane_b32 s1, v254, 2
	s_branch .LBB0_665

; #define PG8_STAGE(bufoff, gbase, voff) do { _Pragma("unroll") for (int _i = 0; _i < 2; ++_i) \
;         __builtin_amdgcn_global_load_lds((const unsigned*)((const char*)(gbase) + (voff)[_i]), (PG8_LAS unsigned*)(lds + (bufoff) + ldsw + _i * 8192), 16, 0, 0); } while (0)
; #define PG8_WAIT_V(n) asm volatile("s_waitcnt vmcnt(" #n ")" ::: "memory")
; #define PG8_BAR __builtin_amdgcn_s_barrier()
; template <class Epi, class Sched, bool ALIGN_EPI = false, bool SP2 = false>
; __device__ __forceinline__ void gemm_phase(PG8_LAS unsigned char* lds, const Gemm g, const Sched& S, const Epi& E) {
;     ...
;     for (int i = 0; i < 2; ++i) { int R, C; stage_rc(tid * 16 + i * 8192, R, C); const int Rb = Epi::PERM ? ((R & ~31) + perm32(R & 31)) : R;
;         voffA[i] = (unsigned)(R * g.lda + C) * 2u; voffB[i] = (unsigned)(Rb * g.ldb + C) * 2u; }
;     const size_t kstep = (size_t)(BK * 2);
;     const size_t hstepA = (size_t)HALF * g.lda * 2, hstepB = (size_t)HALF * g.ldb * 2;
;     const size_t tstepA = 2 * hstepA, tstepB = 2 * hstepB;
;     const unsigned ldsw = (unsigned)wid * 1024u;
;     const int aoff = lds_byte(wr * 64 + fr, fq * 8), boff = lds_byte(wc * 32 + fr, fq * 8);
;     ...
;         PG8_STAGE(PG8_SB(0, 0), cB, voffB); PG8_STAGE(PG8_SB(0, 1), cB + hstepB, voffB); PG8_STAGE(PG8_SA(0, 0), cA, voffA); PG8_STAGE(PG8_SA(0, 1), cA + hstepA, voffA);
;         if (wr == 1) PG8_BAR;
;         PG8_WAIT_V(2); PG8_BAR;
;         PG8_STAGE(PG8_SB(1, 0), cB + kstep, voffB); PG8_STAGE(PG8_SA(1, 0), cA + kstep, voffA); PG8_STAGE(PG8_SB(1, 1), cB + hstepB + kstep, voffB);
;         PG8_WAIT_V(6); PG8_BAR;
.LBB0_683:
	v_readlane_b32 s84, v254, 28
	s_lshl_b32 s1, s1, 5
	v_readlane_b32 s85, v254, 29
	v_and_b32_e32 v7, 48, v6
	v_lshlrev_b32_e32 v16, 6, v6
	s_movk_i32 s3, 0x3c0
	v_lshlrev_b32_e32 v6, 2, v6
	s_and_b32 s62, s1, 0x60
	v_lshl_add_u64 v[8:9], s[84:85], 0, v[192:193]
	v_mov_b32_e32 v157, v193
	v_readlane_b32 s4, v254, 30
	s_lshl_b32 s49, s2, 6
	s_lshl_b32 s2, s2, 13
	v_and_or_b32 v7, v16, s3, v7
	v_and_b32_e32 v6, 32, v6
	s_lshl_b32 s1, s62, 7
	v_lshl_add_u64 v[10:11], s[84:85], 0, v[156:157]
	v_mov_b32_e32 v161, v193
	v_readlane_b32 s5, v254, 31
	v_bitop3_b32 v16, v7, s2, v6 bitop3:0xde
	v_bitop3_b32 v182, s1, v7, v6 bitop3:0xf6
	s_add_i32 m0, s20, 0x18000
	v_lshl_add_u64 v[6:7], v[8:9], 0, s[36:37]
	v_lshl_add_u64 v[12:13], s[4:5], 0, v[160:161]
	v_mov_b32_e32 v159, v193
	global_load_lds_dwordx4 v[6:7], off
	v_lshl_add_u64 v[6:7], v[10:11], 0, s[36:37]
	s_add_i32 m0, s20, 0x1a000
	s_add_i32 s63, s20, 0x8000
	v_lshl_add_u64 v[14:15], s[4:5], 0, v[158:159]
	global_load_lds_dwordx4 v[6:7], off
	v_lshl_add_u64 v[6:7], v[12:13], 0, s[36:37]
	s_mov_b32 m0, s63
	s_add_i32 s64, s20, 0xa000
	v_readlane_b32 s2, v254, 53
	global_load_lds_dwordx4 v[6:7], off
	v_lshl_add_u64 v[6:7], v[14:15], 0, s[36:37]
	s_mov_b32 m0, s64
	v_readlane_b32 s3, v254, 54
	global_load_lds_dwordx4 v[6:7], off
	s_add_i32 m0, s20, 0x1c000
	v_lshl_add_u64 v[6:7], s[2:3], 0, v[192:193]
	global_load_lds_dwordx4 v[6:7], off
	v_lshl_add_u64 v[6:7], s[2:3], 0, v[156:157]
	s_add_i32 m0, s20, 0x1e000
	s_cmpk_lt_u32 s0, 0x100
	global_load_lds_dwordx4 v[6:7], off
	s_waitcnt vmcnt(8)
	s_barrier
	v_lshlrev_b32_e32 v6, 14, v0
	v_and_b32_e32 v6, 0xffff8000, v6
	v_lshl_add_u32 v1, v1, 11, v6
	v_and_b32_e32 v0, 1, v0
	v_lshl_or_b32 v0, v0, 6, v1
	v_lshl_add_u32 v162, v2, 1, v0
	v_lshlrev_b32_e32 v0, 14, v4
	v_and_b32_e32 v0, 0xffff8000, v0
	s_waitcnt vmcnt(6)
	v_lshl_add_u32 v0, v3, 11, v0
	v_and_b32_e32 v1, 1, v4
	v_lshl_or_b32 v0, v1, 6, v0
	v_readlane_b32 s0, v254, 36
	s_cselect_b64 s[12:13], -1, 0
	v_mov_b32_e32 v163, v193
	v_lshl_add_u32 v164, v5, 1, v0
	v_mov_b32_e32 v165, v193
	s_mov_b32 s65, 0
	v_add_u32_e32 v183, 0, v16
	v_readlane_b32 s80, v254, 48
	s_mov_b32 s88, s0
	s_barrier
	v_readlane_b32 s1, v254, 37
	s_branch .LBB0_686

; #define PG8_STAGE(bufoff, gbase, voff) do { _Pragma("unroll") for (int _i = 0; _i < 2; ++_i) \
;         __builtin_amdgcn_global_load_lds((const unsigned*)((const char*)(gbase) + (voff)[_i]), (PG8_LAS unsigned*)(lds + (bufoff) + ldsw + _i * 8192), 16, 0, 0); } while (0)
; #define PG8_WAIT_V(n) asm volatile("s_waitcnt vmcnt(" #n ")" ::: "memory")
; #define PG8_BAR __builtin_amdgcn_s_barrier()
; template <class Epi, class Sched, bool ALIGN_EPI = false, bool SP2 = false>
; __device__ __forceinline__ void gemm_phase(PG8_LAS unsigned char* lds, const Gemm g, const Sched& S, const Epi& E) {
;     ...
;     for (int i = 0; i < 2; ++i) { int R, C; stage_rc(tid * 16 + i * 8192, R, C); const int Rb = Epi::PERM ? ((R & ~31) + perm32(R & 31)) : R;
;         voffA[i] = (unsigned)(R * g.lda + C) * 2u; voffB[i] = (unsigned)(Rb * g.ldb + C) * 2u; }
;     const size_t kstep = (size_t)(BK * 2);
;     const size_t hstepA = (size_t)HALF * g.lda * 2, hstepB = (size_t)HALF * g.ldb * 2;
;     const size_t tstepA = 2 * hstepA, tstepB = 2 * hstepB;
;     const unsigned ldsw = (unsigned)wid * 1024u;
;     const int aoff = lds_byte(wr * 64 + fr, fq * 8), boff = lds_byte(wc * 32 + fr, fq * 8);
;     ...
;         PG8_STAGE(PG8_SB(0, 0), cB, voffB); PG8_STAGE(PG8_SB(0, 1), cB + hstepB, voffB); PG8_STAGE(PG8_SA(0, 0), cA, voffA); PG8_STAGE(PG8_SA(0, 1), cA + hstepA, voffA);
;         if (wr == 1) PG8_BAR;
;         PG8_WAIT_V(2); PG8_BAR;
;         PG8_STAGE(PG8_SB(1, 0), cB + kstep, voffB); PG8_STAGE(PG8_SA(1, 0), cA + kstep, voffA); PG8_STAGE(PG8_SB(1, 1), cB + hstepB + kstep, voffB);
;         PG8_WAIT_V(6); PG8_BAR;
.LBB0_710:
	v_readlane_b32 s14, v253, 63
	s_and_b64 s[4:5], s[4:5], exec
	v_readlane_b32 s15, v254, 0
	s_cselect_b32 s4, s25, s59
	s_cselect_b32 s5, s24, s58
	s_cselect_b32 s15, s61, s15
	s_cselect_b32 s14, s60, s14
	s_cselect_b32 s87, 16, 64
	s_add_i32 m0, s64, 0x18000
	v_lshl_add_u64 v[0:1], v[0:1], 0, s[36:37]
	global_load_lds_dwordx4 v[0:1], off
	v_lshl_add_u64 v[0:1], v[2:3], 0, s[36:37]
	s_add_i32 m0, s64, 0x1a000
	s_add_i32 s91, s64, 0x8000
	global_load_lds_dwordx4 v[0:1], off
	v_lshl_add_u64 v[0:1], v[8:9], 0, s[36:37]
	s_mov_b32 m0, s91
	s_add_i32 s92, s64, 0xa000
	global_load_lds_dwordx4 v[0:1], off
	v_lshl_add_u64 v[0:1], v[10:11], 0, s[36:37]
	s_mov_b32 m0, s92
	s_and_b32 s88, s6, 3
	global_load_lds_dwordx4 v[0:1], off
	s_add_i32 m0, s64, 0x1c000
	v_lshl_add_u64 v[0:1], v[4:5], 0, s[36:37]
	global_load_lds_dwordx4 v[0:1], off
	v_lshl_add_u64 v[0:1], v[6:7], 0, s[36:37]
	s_add_i32 m0, s64, 0x1e000
	v_and_b32_e32 v19, 48, v18
	global_load_lds_dwordx4 v[0:1], off
	s_waitcnt vmcnt(8)
	s_barrier
	v_lshlrev_b32_e32 v20, 6, v18
	s_movk_i32 s6, 0x3c0
	v_lshlrev_b32_e32 v18, 2, v18
	s_lshl_b32 s89, s3, 6
	s_lshl_b32 s3, s3, 13
	v_and_or_b32 v19, v20, s6, v19
	v_and_b32_e32 v18, 32, v18
	v_bitop3_b32 v20, v19, s3, v18 bitop3:0xde
	s_lshl_b32 s90, s88, 5
	s_lshl_b32 s3, s88, 12
	s_add_i32 s93, s87, -2
	v_add_u32_e32 v0, v14, v12
	s_cmpk_lt_u32 s2, 0x100
	v_add_lshl_u32 v0, v0, v13, 1
	v_mov_b32_e32 v1, v193
	s_waitcnt vmcnt(6)
	s_cselect_b64 s[16:17], -1, 0
	s_lshl_b32 s2, s88, 6
	v_lshl_add_u64 v[204:205], s[10:11], 0, v[0:1]
	v_add_u32_e32 v0, v17, v15
	v_bitop3_b32 v247, v19, s3, v18 bitop3:0xde
	s_add_u32 s94, s5, s2
	v_add_lshl_u32 v0, v0, v16, 1
	v_readlane_b32 s2, v254, 1
	s_addc_u32 s95, s4, 0
	v_lshl_add_u64 v[206:207], s[10:11], 0, v[0:1]
	s_mov_b32 s11, 0
	v_add_u32_e32 v248, 0, v20
	v_readlane_b32 s34, v254, 16
	s_mov_b32 s97, s2
	s_barrier
	v_readlane_b32 s3, v254, 2
	s_branch .LBB0_713

; #define PG8_STAGE(bufoff, gbase, voff) do { _Pragma("unroll") for (int _i = 0; _i < 2; ++_i) \
;         __builtin_amdgcn_global_load_lds((const unsigned*)((const char*)(gbase) + (voff)[_i]), (PG8_LAS unsigned*)(lds + (bufoff) + ldsw + _i * 8192), 16, 0, 0); } while (0)
; #define PG8_WAIT_V(n) asm volatile("s_waitcnt vmcnt(" #n ")" ::: "memory")
; #define PG8_BAR __builtin_amdgcn_s_barrier()
; template <class Epi, class Sched, bool ALIGN_EPI = false, bool SP2 = false>
; __device__ __forceinline__ void gemm_phase(PG8_LAS unsigned char* lds, const Gemm g, const Sched& S, const Epi& E) {
;     ...
;     for (int i = 0; i < 2; ++i) { int R, C; stage_rc(tid * 16 + i * 8192, R, C); const int Rb = Epi::PERM ? ((R & ~31) + perm32(R & 31)) : R;
;         voffA[i] = (unsigned)(R * g.lda + C) * 2u; voffB[i] = (unsigned)(Rb * g.ldb + C) * 2u; }
;     const size_t kstep = (size_t)(BK * 2);
;     const size_t hstepA = (size_t)HALF * g.lda * 2, hstepB = (size_t)HALF * g.ldb * 2;
;     const size_t tstepA = 2 * hstepA, tstepB = 2 * hstepB;
;     const unsigned ldsw = (unsigned)wid * 1024u;
;     const int aoff = lds_byte(wr * 64 + fr, fq * 8), boff = lds_byte(wc * 32 + fr, fq * 8);
;     ...
;         PG8_STAGE(PG8_SB(0, 0), cB, voffB); PG8_STAGE(PG8_SB(0, 1), cB + hstepB, voffB); PG8_STAGE(PG8_SA(0, 0), cA, voffA); PG8_STAGE(PG8_SA(0, 1), cA + hstepA, voffA);
;         if (wr == 1) PG8_BAR;
;         PG8_WAIT_V(2); PG8_BAR;
;         PG8_STAGE(PG8_SB(1, 0), cB + kstep, voffB); PG8_STAGE(PG8_SA(1, 0), cA + kstep, voffA); PG8_STAGE(PG8_SB(1, 1), cB + hstepB + kstep, voffB);
;         PG8_WAIT_V(6); PG8_BAR;
.LBB0_752:
	s_add_i32 m0, s62, 0x18000
	v_lshl_add_u64 v[0:1], v[0:1], 0, s[36:37]
	global_load_lds_dwordx4 v[0:1], off
	v_lshl_add_u64 v[0:1], v[2:3], 0, s[36:37]
	s_add_i32 m0, s62, 0x1a000
	s_add_i32 s86, s62, 0x8000
	global_load_lds_dwordx4 v[0:1], off
	v_lshl_add_u64 v[0:1], v[8:9], 0, s[36:37]
	s_mov_b32 m0, s86
	s_add_i32 s87, s62, 0xa000
	global_load_lds_dwordx4 v[0:1], off
	v_lshl_add_u64 v[0:1], v[10:11], 0, s[36:37]
	s_mov_b32 m0, s87
	s_lshr_b32 s80, s1, 6
	global_load_lds_dwordx4 v[0:1], off
	s_add_i32 m0, s62, 0x1c000
	v_lshl_add_u64 v[0:1], v[4:5], 0, s[36:37]
	global_load_lds_dwordx4 v[0:1], off
	v_lshl_add_u64 v[0:1], v[6:7], 0, s[36:37]
	s_add_i32 m0, s62, 0x1e000
	s_lshl_b32 s84, s3, 6
	global_load_lds_dwordx4 v[0:1], off
	s_waitcnt vmcnt(8)
	s_barrier
	v_and_b32_e32 v21, 48, v20
	s_lshl_b32 s1, s3, 13
	v_lshlrev_b32_e32 v22, 6, v20
	s_movk_i32 s3, 0x3c0
	v_lshlrev_b32_e32 v20, 2, v20
	v_and_or_b32 v21, v22, s3, v21
	v_and_b32_e32 v20, 32, v20
	v_bitop3_b32 v22, v21, s1, v20 bitop3:0xde
	s_lshl_b32 s1, s2, 5
	s_and_b32 s85, s1, 0x60
	s_movk_i32 s2, 0x1300
	s_lshl_b32 s1, s85, 7
	s_add_i32 s88, s80, -2
	v_lshrrev_b32_e32 v1, 1, v12
	v_mul_lo_u32 v0, v13, s2
	s_mov_b32 s3, 0x13000
	v_bitop3_b32 v222, s1, v21, v20 bitop3:0xf6
	s_cmpk_lt_u32 s0, 0x100
	v_mad_u64_u32 v[0:1], s[0:1], v1, s3, v[0:1]
	v_or_b32_e32 v0, v0, v14
	v_add_lshl_u32 v0, v0, v15, 1
	v_mov_b32_e32 v1, v193
	s_mov_b64 s[4:5], 0x130080
	v_lshl_add_u64 v[204:205], v[0:1], 0, s[4:5]
	v_lshrrev_b32_e32 v1, 1, v17
	v_mul_lo_u32 v0, v16, s2
	v_mad_u64_u32 v[0:1], s[0:1], v1, s3, v[0:1]
	s_waitcnt vmcnt(6)
	v_or_b32_e32 v0, v0, v18
	v_add_lshl_u32 v0, v0, v19, 1
	v_mov_b32_e32 v1, v193
	v_readlane_b32 s0, v254, 1
	s_cselect_b64 s[12:13], -1, 0
	v_lshl_add_u64 v[206:207], v[0:1], 0, s[4:5]
	s_mov_b32 s89, 0
	v_add_u32_e32 v223, 0, v22
	v_readlane_b32 s78, v254, 16
	s_mov_b32 s92, s0
	s_barrier
	v_readlane_b32 s1, v254, 2
	s_branch .LBB0_755

; #define PG8_STAGE(bufoff, gbase, voff) do { _Pragma("unroll") for (int _i = 0; _i < 2; ++_i) \
;         __builtin_amdgcn_global_load_lds((const unsigned*)((const char*)(gbase) + (voff)[_i]), (PG8_LAS unsigned*)(lds + (bufoff) + ldsw + _i * 8192), 16, 0, 0); } while (0)
; #define PG8_WAIT_V(n) asm volatile("s_waitcnt vmcnt(" #n ")" ::: "memory")
; #define PG8_BAR __builtin_amdgcn_s_barrier()
; template <class Epi, class Sched, bool ALIGN_EPI = false, bool SP2 = false>
; __device__ __forceinline__ void gemm_phase(PG8_LAS unsigned char* lds, const Gemm g, const Sched& S, const Epi& E) {
;     ...
;     for (int i = 0; i < 2; ++i) { int R, C; stage_rc(tid * 16 + i * 8192, R, C); const int Rb = Epi::PERM ? ((R & ~31) + perm32(R & 31)) : R;
;         voffA[i] = (unsigned)(R * g.lda + C) * 2u; voffB[i] = (unsigned)(Rb * g.ldb + C) * 2u; }
;     const size_t kstep = (size_t)(BK * 2);
;     const size_t hstepA = (size_t)HALF * g.lda * 2, hstepB = (size_t)HALF * g.ldb * 2;
;     const size_t tstepA = 2 * hstepA, tstepB = 2 * hstepB;
;     const unsigned ldsw = (unsigned)wid * 1024u;
;     const int aoff = lds_byte(wr * 64 + fr, fq * 8), boff = lds_byte(wc * 32 + fr, fq * 8);
;     ...
;         PG8_STAGE(PG8_SB(0, 0), cB, voffB); PG8_STAGE(PG8_SB(0, 1), cB + hstepB, voffB); PG8_STAGE(PG8_SA(0, 0), cA, voffA); PG8_STAGE(PG8_SA(0, 1), cA + hstepA, voffA);
;         if (wr == 1) PG8_BAR;
;         PG8_WAIT_V(2); PG8_BAR;
;         PG8_STAGE(PG8_SB(1, 0), cB + kstep, voffB); PG8_STAGE(PG8_SA(1, 0), cA + kstep, voffA); PG8_STAGE(PG8_SB(1, 1), cB + hstepB + kstep, voffB);
;         PG8_WAIT_V(6); PG8_BAR;
.LBB0_811:
	s_and_b32 s3, s3, 3
	s_add_i32 m0, s19, 0x18000
	v_lshl_add_u64 v[6:7], v[6:7], 0, s[36:37]
	s_lshl_b32 s49, s4, 6
	s_lshl_b32 s7, s4, 13
	s_lshl_b32 s20, s3, 5
	s_lshl_b32 s3, s3, 12
	global_load_lds_dwordx4 v[6:7], off
	v_lshl_add_u64 v[4:5], v[4:5], 0, s[36:37]
	s_add_i32 m0, s19, 0x1a000
	s_add_i32 s21, s19, 0x8000
	s_add_i32 s62, s19, 0xa000
	global_load_lds_dwordx4 v[4:5], off
	v_lshl_add_u64 v[0:1], v[0:1], 0, s[36:37]
	s_mov_b32 m0, s21
	s_add_u32 s4, s0, 0x40080
	global_load_lds_dwordx4 v[0:1], off
	v_lshl_add_u64 v[0:1], v[2:3], 0, s[36:37]
	s_mov_b32 m0, s62
	s_addc_u32 s5, s1, 0
	global_load_lds_dwordx4 v[0:1], off
	s_add_i32 m0, s19, 0x1c000
	v_lshl_add_u64 v[0:1], s[4:5], 0, v[192:193]
	global_load_lds_dwordx4 v[0:1], off
	v_lshl_add_u64 v[0:1], s[4:5], 0, v[202:203]
	s_add_i32 m0, s19, 0x1e000
	s_movk_i32 s4, 0x3c0
	global_load_lds_dwordx4 v[0:1], off
	s_waitcnt vmcnt(8)
	s_barrier
	v_and_b32_e32 v0, 48, v8
	v_lshlrev_b32_e32 v1, 6, v8
	v_and_or_b32 v0, v1, s4, v0
	v_lshlrev_b32_e32 v1, 2, v8
	v_and_b32_e32 v1, 32, v1
	v_bitop3_b32 v2, v0, s7, v1 bitop3:0xde
	v_bitop3_b32 v240, v0, s3, v1 bitop3:0xde
	v_lshlrev_b32_e32 v0, 14, v12
	v_and_b32_e32 v0, 0xffff8000, v0
	v_lshl_add_u32 v0, v13, 11, v0
	v_and_b32_e32 v1, 1, v12
	v_lshl_or_b32 v0, v1, 6, v0
	v_lshl_add_u32 v204, v14, 1, v0
	v_lshlrev_b32_e32 v0, 14, v9
	v_and_b32_e32 v0, 0xffff8000, v0
	s_waitcnt vmcnt(6)
	s_cmpk_lt_u32 s2, 0x100
	v_lshl_add_u32 v0, v10, 11, v0
	v_and_b32_e32 v1, 1, v9
	s_cselect_b64 s[66:67], -1, 0
	s_bitcmp0_b32 s2, 6
	v_lshl_or_b32 v0, v1, 6, v0
	s_mov_b32 s63, 0
	s_cselect_b64 s[96:97], -1, 0
	v_mov_b32_e32 v205, v193
	v_lshl_add_u32 v206, v11, 1, v0
	v_mov_b32_e32 v207, v193
	v_add_u32_e32 v241, 0, v2
	s_barrier
	s_branch .LBB0_814
